# GEMM loops: per-phase s_setprio flips deleted, one static s_setprio 1 for waves 4-7 per GEMM phase
# speedup vs baseline: 1.0164x; 1.0050x over previous
.LBB0_241:
	s_andn2_b64 vcc, exec, s[0:1]
	s_cbranch_vccnz .LBB0_266
	v_readlane_b32 s0, v251, 18
	s_waitcnt vmcnt(0)
	v_mov_b32_e32 v7, v160
	v_readlane_b32 s1, v251, 19
	s_andn2_b64 vcc, exec, s[0:1]
	v_readfirstlane_b32 s22, v7
	s_cbranch_vccnz .LBB0_266
	s_waitcnt vmcnt(0)
	v_lshlrev_b32_e32 v4, 4, v7
	v_add_u32_e32 v2, 0x2000, v4
	v_ashrrev_i32_e32 v0, 31, v2
	v_lshrrev_b32_e32 v0, 22, v0
	v_add_u32_e32 v0, v2, v0
	v_ashrrev_i32_e32 v0, 10, v0
	v_mul_i32_i24_e32 v3, 0x400, v0
	v_sub_u32_e32 v2, v2, v3
	v_lshrrev_b32_e32 v3, 4, v2
	v_bitop3_b32 v3, v3, v2, 32 bitop3:0x6c
	v_ashrrev_i32_e32 v2, 31, v3
	v_lshrrev_b32_e32 v2, 26, v2
	v_add_u32_e32 v5, v3, v2
	v_lshlrev_b32_e32 v6, 3, v0
	v_ashrrev_i32_e32 v2, 6, v5
	v_and_b32_e32 v6, -16, v6
	v_add_u32_e32 v6, v2, v6
	v_and_b32_e32 v8, 3, v2
	s_mov_b32 s1, 0x1fffe0
	v_lshrrev_b32_e32 v9, 2, v6
	v_lshlrev_b32_e32 v10, 1, v6
	v_and_b32_e32 v5, 0xc0, v5
	v_and_or_b32 v8, v6, s1, v8
	v_and_b32_e32 v9, 4, v9
	v_and_b32_e32 v10, 24, v10
	v_sub_u32_e32 v3, v3, v5
	v_or3_b32 v8, v8, v9, v10
	v_lshlrev_b32_e32 v9, 5, v0
	v_ashrrev_i16_sdwa v3, v243, sext(v3) dst_sel:DWORD dst_unused:UNUSED_PAD src0_sel:DWORD src1_sel:BYTE_0
	v_and_b32_e32 v9, 32, v9
	v_bfe_i32 v3, v3, 0, 16
	v_add_lshl_u32 v5, v9, v3, 1
	v_lshl_add_u32 v144, v8, 11, v5
	v_lshl_add_u32 v146, v6, 11, v5
	v_bfe_i32 v5, v7, 27, 1
	v_lshrrev_b32_e32 v5, 22, v5
	v_add_u32_e32 v5, v4, v5
	v_and_b32_e32 v5, 0xfffffc00, v5
	v_sub_u32_e32 v4, v4, v5
	v_lshrrev_b32_e32 v5, 4, v4
	v_bitop3_b32 v6, v5, v4, 32 bitop3:0x6c
	v_ashrrev_i32_e32 v5, 31, v7
	v_lshrrev_b32_e32 v5, 26, v5
	v_ashrrev_i32_e32 v4, 31, v6
	v_add_u32_e32 v5, v7, v5
	v_lshrrev_b32_e32 v4, 26, v4
	v_ashrrev_i32_e32 v5, 6, v5
	v_add_u32_e32 v8, v6, v4
	v_lshlrev_b32_e32 v9, 3, v5
	v_ashrrev_i32_e32 v4, 6, v8
	v_and_b32_e32 v9, -16, v9
	v_add_u32_e32 v9, v4, v9
	v_and_b32_e32 v10, 3, v4
	v_lshrrev_b32_e32 v11, 2, v9
	v_lshlrev_b32_e32 v12, 1, v9
	v_and_b32_e32 v8, 0xc0, v8
	v_and_or_b32 v10, v9, s1, v10
	v_and_b32_e32 v11, 4, v11
	v_and_b32_e32 v12, 24, v12
	v_sub_u32_e32 v6, v6, v8
	s_ashr_i32 s0, s22, 6
	v_or3_b32 v10, v10, v11, v12
	v_lshlrev_b32_e32 v11, 5, v5
	v_ashrrev_i16_sdwa v6, v243, sext(v6) dst_sel:DWORD dst_unused:UNUSED_PAD src0_sel:DWORD src1_sel:BYTE_0
	s_lshl_b32 s23, s0, 10
	v_and_b32_e32 v11, 32, v11
	v_bfe_i32 v6, v6, 0, 16
	v_add_lshl_u32 v8, v11, v6, 1
	s_add_i32 s33, s23, 0
	v_readlane_b32 s2, v253, 56
	v_lshl_add_u32 v148, v10, 11, v8
	s_add_i32 m0, s33, 0x10000
	v_readlane_b32 s3, v253, 57
	v_lshl_add_u32 v150, v9, 11, v8
	s_add_i32 s35, s33, 0x2000
	s_add_i32 s41, s33, 0x4000
	s_add_i32 s44, s33, 0x6000
	s_ashr_i32 s1, s22, 8
	global_load_lds_dwordx4 v148, s[2:3]
	s_add_i32 m0, s33, 0x12000
	s_nop 0
	global_load_lds_dwordx4 v144, s[2:3]
	v_readlane_b32 s2, v253, 52
	s_mov_b32 m0, s33
	v_readlane_b32 s3, v253, 53
	s_nop 4
	global_load_lds_dwordx4 v150, s[2:3]
	s_mov_b32 m0, s35
	s_nop 0
	global_load_lds_dwordx4 v146, s[2:3]
	v_readlane_b32 s2, v253, 50
	s_add_i32 m0, s33, 0x14000
	v_readlane_b32 s3, v253, 51
	s_nop 4
	global_load_lds_dwordx4 v148, s[2:3]
	s_add_i32 m0, s33, 0x16000
	s_cmp_lg_u32 s1, 1
	global_load_lds_dwordx4 v144, s[2:3]
	v_readlane_b32 s2, v253, 54
	s_mov_b32 m0, s41
	v_readlane_b32 s3, v253, 55
	s_nop 4
	global_load_lds_dwordx4 v150, s[2:3]
	s_mov_b32 m0, s44
	s_nop 0
	global_load_lds_dwordx4 v146, s[2:3]
	s_cbranch_scc1 .LBB0_245
	s_setprio 1
	s_barrier

.LBB0_254:
	s_add_u32 s2, s20, 0xfffc0080
	s_addc_u32 s3, s21, -1
	s_add_i32 s70, 0, 0x10000
	v_add_u32_e32 v0, s70, v143
	ds_read_b128 v[156:159], v0
	ds_read_b128 v[170:173], v0 offset:1024
	ds_read_b128 v[174:177], v0 offset:2048
	ds_read_b128 v[178:181], v0 offset:3072
	s_cmp_eq_u32 s69, 12
	s_cselect_b32 s29, s31, s3
	s_cselect_b32 s28, s65, s2
	s_cselect_b32 s3, s1, s68
	s_cselect_b32 s2, s66, s67
	v_lshl_add_u64 v[130:131], s[20:21], 0, v[152:153]
	s_add_i32 m0, s33, 0xc000
	ds_read_b128 v[182:185], v169
	ds_read_b128 v[186:189], v169 offset:1024
	ds_read_b128 v[190:193], v169 offset:2048
	ds_read_b128 v[194:197], v169 offset:3072
	ds_read_b128 v[198:201], v169 offset:4096
	ds_read_b128 v[202:205], v169 offset:5120
	ds_read_b128 v[206:209], v169 offset:6144
	ds_read_b128 v[210:213], v169 offset:7168
	global_load_lds_dwordx4 v[130:131], off
	v_lshl_add_u64 v[130:131], s[20:21], 0, v[154:155]
	s_add_i32 m0, s33, 0xe000
	s_nop 0
	global_load_lds_dwordx4 v[130:131], off
	s_waitcnt lgkmcnt(8)
	s_barrier
	s_waitcnt lgkmcnt(0)
	v_mfma_f32_16x16x32_bf16 v[126:129], v[156:159], v[182:185], v[126:129]
	v_mfma_f32_16x16x32_bf16 v[122:125], v[174:177], v[182:185], v[122:125]
	v_mfma_f32_16x16x32_bf16 v[110:113], v[156:159], v[190:193], v[110:113]
	v_mfma_f32_16x16x32_bf16 v[106:109], v[174:177], v[190:193], v[106:109]
	v_mfma_f32_16x16x32_bf16 v[94:97], v[156:159], v[198:201], v[94:97]
	v_mfma_f32_16x16x32_bf16 v[90:93], v[174:177], v[198:201], v[90:93]
	v_mfma_f32_16x16x32_bf16 v[78:81], v[156:159], v[206:209], v[78:81]
	v_mfma_f32_16x16x32_bf16 v[74:77], v[174:177], v[206:209], v[74:77]
	v_mfma_f32_16x16x32_bf16 v[126:129], v[170:173], v[186:189], v[126:129]
	v_mfma_f32_16x16x32_bf16 v[122:125], v[178:181], v[186:189], v[122:125]
	v_mfma_f32_16x16x32_bf16 v[110:113], v[170:173], v[194:197], v[110:113]
	v_mfma_f32_16x16x32_bf16 v[106:109], v[178:181], v[194:197], v[106:109]
	v_mfma_f32_16x16x32_bf16 v[94:97], v[170:173], v[202:205], v[94:97]
	v_mfma_f32_16x16x32_bf16 v[90:93], v[178:181], v[202:205], v[90:93]
	v_mfma_f32_16x16x32_bf16 v[78:81], v[170:173], v[210:213], v[78:81]
	v_mfma_f32_16x16x32_bf16 v[74:77], v[178:181], v[210:213], v[74:77]
	s_barrier
	s_add_i32 s72, 0, 0x14000
	s_add_i32 s70, s70, s23
	v_add_u32_e32 v0, s72, v143
	v_lshl_add_u64 v[130:131], s[2:3], 0, v[148:149]
	s_mov_b32 m0, s70
	ds_read_b128 v[214:217], v0
	ds_read_b128 v[218:221], v0 offset:1024
	ds_read_b128 v[222:225], v0 offset:2048
	ds_read_b128 v[226:229], v0 offset:3072
	global_load_lds_dwordx4 v[130:131], off
	v_lshl_add_u64 v[132:133], s[2:3], 0, v[144:145]
	s_add_i32 m0, s70, 0x2000
	s_nop 0
	global_load_lds_dwordx4 v[132:133], off
	s_barrier
	s_waitcnt lgkmcnt(0)
	v_mfma_f32_16x16x32_bf16 v[118:121], v[214:217], v[182:185], v[118:121]
	v_mfma_f32_16x16x32_bf16 v[114:117], v[222:225], v[182:185], v[114:117]
	v_mfma_f32_16x16x32_bf16 v[102:105], v[214:217], v[190:193], v[102:105]
	v_mfma_f32_16x16x32_bf16 v[98:101], v[222:225], v[190:193], v[98:101]
	v_mfma_f32_16x16x32_bf16 v[86:89], v[214:217], v[198:201], v[86:89]
	v_mfma_f32_16x16x32_bf16 v[82:85], v[222:225], v[198:201], v[82:85]
	v_mfma_f32_16x16x32_bf16 v[70:73], v[214:217], v[206:209], v[70:73]
	v_mfma_f32_16x16x32_bf16 v[66:69], v[222:225], v[206:209], v[66:69]
	v_mfma_f32_16x16x32_bf16 v[118:121], v[218:221], v[186:189], v[118:121]
	v_mfma_f32_16x16x32_bf16 v[114:117], v[226:229], v[186:189], v[114:117]
	v_mfma_f32_16x16x32_bf16 v[102:105], v[218:221], v[194:197], v[102:105]
	v_mfma_f32_16x16x32_bf16 v[98:101], v[226:229], v[194:197], v[98:101]
	v_mfma_f32_16x16x32_bf16 v[86:89], v[218:221], v[202:205], v[86:89]
	v_mfma_f32_16x16x32_bf16 v[82:85], v[226:229], v[202:205], v[82:85]
	v_mfma_f32_16x16x32_bf16 v[70:73], v[218:221], v[210:213], v[70:73]
	v_mfma_f32_16x16x32_bf16 v[66:69], v[226:229], v[210:213], v[66:69]
	s_mov_b32 m0, s33
	v_lshl_add_u64 v[162:163], s[28:29], 0, v[150:151]
	s_barrier
	ds_read_b128 v[182:185], v169 offset:16384
	ds_read_b128 v[186:189], v169 offset:17408
	ds_read_b128 v[190:193], v169 offset:18432
	ds_read_b128 v[194:197], v169 offset:19456
	ds_read_b128 v[198:201], v169 offset:20480
	ds_read_b128 v[202:205], v169 offset:21504
	ds_read_b128 v[206:209], v169 offset:22528
	ds_read_b128 v[210:213], v169 offset:23552
	global_load_lds_dwordx4 v[162:163], off
	v_lshl_add_u64 v[164:165], s[28:29], 0, v[146:147]
	s_mov_b32 m0, s35
	s_nop 0
	global_load_lds_dwordx4 v[164:165], off
	s_barrier
	s_waitcnt lgkmcnt(0)
	v_mfma_f32_16x16x32_bf16 v[62:65], v[156:159], v[182:185], v[62:65]
	v_mfma_f32_16x16x32_bf16 v[58:61], v[174:177], v[182:185], v[58:61]
	v_mfma_f32_16x16x32_bf16 v[50:53], v[156:159], v[190:193], v[50:53]
	v_mfma_f32_16x16x32_bf16 v[42:45], v[174:177], v[190:193], v[42:45]
	v_mfma_f32_16x16x32_bf16 v[34:37], v[156:159], v[198:201], v[34:37]
	v_mfma_f32_16x16x32_bf16 v[26:29], v[174:177], v[198:201], v[26:29]
	v_mfma_f32_16x16x32_bf16 v[18:21], v[156:159], v[206:209], v[18:21]
	v_mfma_f32_16x16x32_bf16 v[10:13], v[174:177], v[206:209], v[10:13]
	v_mfma_f32_16x16x32_bf16 v[62:65], v[170:173], v[186:189], v[62:65]
	v_mfma_f32_16x16x32_bf16 v[58:61], v[178:181], v[186:189], v[58:61]
	v_mfma_f32_16x16x32_bf16 v[50:53], v[170:173], v[194:197], v[50:53]
	v_mfma_f32_16x16x32_bf16 v[42:45], v[178:181], v[194:197], v[42:45]
	v_mfma_f32_16x16x32_bf16 v[34:37], v[170:173], v[202:205], v[34:37]
	v_mfma_f32_16x16x32_bf16 v[26:29], v[178:181], v[202:205], v[26:29]
	v_mfma_f32_16x16x32_bf16 v[18:21], v[170:173], v[210:213], v[18:21]
	v_mfma_f32_16x16x32_bf16 v[10:13], v[178:181], v[210:213], v[10:13]
	s_barrier
	s_add_u32 s70, s2, 0x40000
	s_addc_u32 s71, s3, 0
	s_add_i32 s72, s72, s23
	v_lshl_add_u64 v[156:157], s[70:71], 0, v[148:149]
	s_mov_b32 m0, s72
	s_nop 0
	global_load_lds_dwordx4 v[156:157], off
	v_lshl_add_u64 v[156:157], s[70:71], 0, v[144:145]
	s_add_i32 m0, s72, 0x2000
	s_nop 0
	global_load_lds_dwordx4 v[156:157], off
	s_waitcnt vmcnt(6)
	s_barrier
	v_mfma_f32_16x16x32_bf16 v[54:57], v[214:217], v[182:185], v[54:57]
	v_mfma_f32_16x16x32_bf16 v[46:49], v[222:225], v[182:185], v[46:49]
	v_mfma_f32_16x16x32_bf16 v[38:41], v[214:217], v[190:193], v[38:41]
	v_mfma_f32_16x16x32_bf16 v[30:33], v[222:225], v[190:193], v[30:33]
	v_mfma_f32_16x16x32_bf16 v[22:25], v[214:217], v[198:201], v[22:25]
	v_mfma_f32_16x16x32_bf16 v[14:17], v[222:225], v[198:201], v[14:17]
	v_mfma_f32_16x16x32_bf16 v[6:9], v[214:217], v[206:209], v[6:9]
	v_mfma_f32_16x16x32_bf16 v[2:5], v[222:225], v[206:209], v[2:5]
	v_mfma_f32_16x16x32_bf16 v[54:57], v[218:221], v[186:189], v[54:57]
	v_mfma_f32_16x16x32_bf16 v[46:49], v[226:229], v[186:189], v[46:49]
	v_mfma_f32_16x16x32_bf16 v[38:41], v[218:221], v[194:197], v[38:41]
	v_mfma_f32_16x16x32_bf16 v[30:33], v[226:229], v[194:197], v[30:33]
	v_mfma_f32_16x16x32_bf16 v[22:25], v[218:221], v[202:205], v[22:25]
	v_mfma_f32_16x16x32_bf16 v[14:17], v[226:229], v[202:205], v[14:17]
	v_mfma_f32_16x16x32_bf16 v[6:9], v[218:221], v[210:213], v[6:9]
	v_mfma_f32_16x16x32_bf16 v[2:5], v[226:229], v[210:213], v[2:5]
	s_add_i32 s70, 0, 0x18000
	v_add_u32_e32 v0, s70, v143
	s_barrier
	ds_read_b128 v[156:159], v0
	ds_read_b128 v[170:173], v0 offset:1024
	ds_read_b128 v[174:177], v0 offset:2048
	ds_read_b128 v[178:181], v0 offset:3072
	s_add_u32 s28, s28, 0x40000
	s_addc_u32 s29, s29, 0
	s_mov_b32 m0, s41
	v_lshl_add_u64 v[214:215], s[28:29], 0, v[150:151]
	ds_read_b128 v[182:185], v169 offset:32768
	ds_read_b128 v[186:189], v169 offset:33792
	ds_read_b128 v[190:193], v169 offset:34816
	ds_read_b128 v[194:197], v169 offset:35840
	ds_read_b128 v[198:201], v169 offset:36864
	ds_read_b128 v[202:205], v169 offset:37888
	ds_read_b128 v[206:209], v169 offset:38912
	ds_read_b128 v[210:213], v169 offset:39936
	global_load_lds_dwordx4 v[214:215], off
	v_lshl_add_u64 v[214:215], s[28:29], 0, v[146:147]
	s_mov_b32 m0, s44
	s_nop 0
	global_load_lds_dwordx4 v[214:215], off
	s_waitcnt lgkmcnt(8)
	s_barrier
	s_waitcnt lgkmcnt(0)
	v_mfma_f32_16x16x32_bf16 v[126:129], v[156:159], v[182:185], v[126:129]
	v_mfma_f32_16x16x32_bf16 v[122:125], v[174:177], v[182:185], v[122:125]
	v_mfma_f32_16x16x32_bf16 v[110:113], v[156:159], v[190:193], v[110:113]
	v_mfma_f32_16x16x32_bf16 v[106:109], v[174:177], v[190:193], v[106:109]
	v_mfma_f32_16x16x32_bf16 v[94:97], v[156:159], v[198:201], v[94:97]
	v_mfma_f32_16x16x32_bf16 v[90:93], v[174:177], v[198:201], v[90:93]
	v_mfma_f32_16x16x32_bf16 v[78:81], v[156:159], v[206:209], v[78:81]
	v_mfma_f32_16x16x32_bf16 v[74:77], v[174:177], v[206:209], v[74:77]
	v_mfma_f32_16x16x32_bf16 v[126:129], v[170:173], v[186:189], v[126:129]
	v_mfma_f32_16x16x32_bf16 v[122:125], v[178:181], v[186:189], v[122:125]
	v_mfma_f32_16x16x32_bf16 v[110:113], v[170:173], v[194:197], v[110:113]
	v_mfma_f32_16x16x32_bf16 v[106:109], v[178:181], v[194:197], v[106:109]
	v_mfma_f32_16x16x32_bf16 v[94:97], v[170:173], v[202:205], v[94:97]
	v_mfma_f32_16x16x32_bf16 v[90:93], v[178:181], v[202:205], v[90:93]
	v_mfma_f32_16x16x32_bf16 v[78:81], v[170:173], v[210:213], v[78:81]
	v_mfma_f32_16x16x32_bf16 v[74:77], v[178:181], v[210:213], v[74:77]
	s_barrier
	s_add_i32 s28, 0, 0x1c000
	s_add_i32 s29, s70, s23
	v_add_u32_e32 v0, s28, v143
	v_lshl_add_u64 v[130:131], v[130:131], 0, s[26:27]
	s_mov_b32 m0, s29
	ds_read_b128 v[214:217], v0
	ds_read_b128 v[218:221], v0 offset:1024
	ds_read_b128 v[222:225], v0 offset:2048
	ds_read_b128 v[226:229], v0 offset:3072
	global_load_lds_dwordx4 v[130:131], off
	v_lshl_add_u64 v[130:131], v[132:133], 0, s[26:27]
	s_add_i32 m0, s29, 0x2000
	s_nop 0
	global_load_lds_dwordx4 v[130:131], off
	s_barrier
	s_waitcnt lgkmcnt(0)
	v_mfma_f32_16x16x32_bf16 v[118:121], v[214:217], v[182:185], v[118:121]
	v_mfma_f32_16x16x32_bf16 v[114:117], v[222:225], v[182:185], v[114:117]
	v_mfma_f32_16x16x32_bf16 v[102:105], v[214:217], v[190:193], v[102:105]
	v_mfma_f32_16x16x32_bf16 v[98:101], v[222:225], v[190:193], v[98:101]
	v_mfma_f32_16x16x32_bf16 v[86:89], v[214:217], v[198:201], v[86:89]
	v_mfma_f32_16x16x32_bf16 v[82:85], v[222:225], v[198:201], v[82:85]
	v_mfma_f32_16x16x32_bf16 v[70:73], v[214:217], v[206:209], v[70:73]
	v_mfma_f32_16x16x32_bf16 v[66:69], v[222:225], v[206:209], v[66:69]
	v_mfma_f32_16x16x32_bf16 v[118:121], v[218:221], v[186:189], v[118:121]
	v_mfma_f32_16x16x32_bf16 v[114:117], v[226:229], v[186:189], v[114:117]
	v_mfma_f32_16x16x32_bf16 v[102:105], v[218:221], v[194:197], v[102:105]
	v_mfma_f32_16x16x32_bf16 v[98:101], v[226:229], v[194:197], v[98:101]
	v_mfma_f32_16x16x32_bf16 v[86:89], v[218:221], v[202:205], v[86:89]
	v_mfma_f32_16x16x32_bf16 v[82:85], v[226:229], v[202:205], v[82:85]
	v_mfma_f32_16x16x32_bf16 v[70:73], v[218:221], v[210:213], v[70:73]
	v_mfma_f32_16x16x32_bf16 v[66:69], v[226:229], v[210:213], v[66:69]
	s_mov_b32 m0, s40
	v_lshl_add_u64 v[130:131], v[162:163], 0, s[26:27]
	s_barrier
	ds_read_b128 v[182:185], v169 offset:49152
	ds_read_b128 v[186:189], v169 offset:50176
	ds_read_b128 v[190:193], v169 offset:51200
	ds_read_b128 v[194:197], v169 offset:52224
	ds_read_b128 v[198:201], v169 offset:53248
	ds_read_b128 v[202:205], v169 offset:54272
	ds_read_b128 v[206:209], v169 offset:55296
	ds_read_b128 v[210:213], v169 offset:56320
	global_load_lds_dwordx4 v[130:131], off
	v_lshl_add_u64 v[130:131], v[164:165], 0, s[26:27]
	s_mov_b32 m0, s45
	s_nop 0
	global_load_lds_dwordx4 v[130:131], off
	s_barrier
	s_waitcnt lgkmcnt(0)
	v_mfma_f32_16x16x32_bf16 v[62:65], v[156:159], v[182:185], v[62:65]
	v_mfma_f32_16x16x32_bf16 v[58:61], v[174:177], v[182:185], v[58:61]
	v_mfma_f32_16x16x32_bf16 v[50:53], v[156:159], v[190:193], v[50:53]
	v_mfma_f32_16x16x32_bf16 v[42:45], v[174:177], v[190:193], v[42:45]
	v_mfma_f32_16x16x32_bf16 v[34:37], v[156:159], v[198:201], v[34:37]
	v_mfma_f32_16x16x32_bf16 v[26:29], v[174:177], v[198:201], v[26:29]
	v_mfma_f32_16x16x32_bf16 v[18:21], v[156:159], v[206:209], v[18:21]
	v_mfma_f32_16x16x32_bf16 v[10:13], v[174:177], v[206:209], v[10:13]
	v_mfma_f32_16x16x32_bf16 v[62:65], v[170:173], v[186:189], v[62:65]
	v_mfma_f32_16x16x32_bf16 v[58:61], v[178:181], v[186:189], v[58:61]
	v_mfma_f32_16x16x32_bf16 v[50:53], v[170:173], v[194:197], v[50:53]
	v_mfma_f32_16x16x32_bf16 v[42:45], v[178:181], v[194:197], v[42:45]
	v_mfma_f32_16x16x32_bf16 v[34:37], v[170:173], v[202:205], v[34:37]
	v_mfma_f32_16x16x32_bf16 v[26:29], v[178:181], v[202:205], v[26:29]
	v_mfma_f32_16x16x32_bf16 v[18:21], v[170:173], v[210:213], v[18:21]
	v_mfma_f32_16x16x32_bf16 v[10:13], v[178:181], v[210:213], v[10:13]
	s_barrier
	s_add_u32 s2, s2, 0x40080
	s_addc_u32 s3, s3, 0
	s_add_i32 s28, s28, s23
	v_lshl_add_u64 v[130:131], s[2:3], 0, v[148:149]
	s_mov_b32 m0, s28
	s_nop 0
	global_load_lds_dwordx4 v[130:131], off
	v_lshl_add_u64 v[130:131], s[2:3], 0, v[144:145]
	s_add_i32 m0, s28, 0x2000
	s_nop 0
	global_load_lds_dwordx4 v[130:131], off
	s_waitcnt vmcnt(6)
	s_barrier
	v_mfma_f32_16x16x32_bf16 v[54:57], v[214:217], v[182:185], v[54:57]
	v_mfma_f32_16x16x32_bf16 v[46:49], v[222:225], v[182:185], v[46:49]
	v_mfma_f32_16x16x32_bf16 v[38:41], v[214:217], v[190:193], v[38:41]
	v_mfma_f32_16x16x32_bf16 v[30:33], v[222:225], v[190:193], v[30:33]
	v_mfma_f32_16x16x32_bf16 v[22:25], v[214:217], v[198:201], v[22:25]
	v_mfma_f32_16x16x32_bf16 v[14:17], v[222:225], v[198:201], v[14:17]
	v_mfma_f32_16x16x32_bf16 v[6:9], v[214:217], v[206:209], v[6:9]
	v_mfma_f32_16x16x32_bf16 v[2:5], v[222:225], v[206:209], v[2:5]
	v_mfma_f32_16x16x32_bf16 v[54:57], v[218:221], v[186:189], v[54:57]
	v_mfma_f32_16x16x32_bf16 v[46:49], v[226:229], v[186:189], v[46:49]
	v_mfma_f32_16x16x32_bf16 v[38:41], v[218:221], v[194:197], v[38:41]
	v_mfma_f32_16x16x32_bf16 v[30:33], v[226:229], v[194:197], v[30:33]
	v_mfma_f32_16x16x32_bf16 v[22:25], v[218:221], v[202:205], v[22:25]
	v_mfma_f32_16x16x32_bf16 v[14:17], v[226:229], v[202:205], v[14:17]
	v_mfma_f32_16x16x32_bf16 v[6:9], v[218:221], v[210:213], v[6:9]
	v_mfma_f32_16x16x32_bf16 v[2:5], v[226:229], v[210:213], v[2:5]
	s_add_i32 s69, s69, 2
	s_add_u32 s20, s20, 0x100
	s_addc_u32 s21, s21, 0
	s_add_u32 s67, s67, 0x100
	s_addc_u32 s68, s68, 0
	s_cmp_gt_u32 s69, 13
	s_barrier
	s_cbranch_scc0 .LBB0_254
	s_add_i32 s1, s47, -4
	v_readlane_b32 s20, v251, 20
	v_lshl_add_u32 v156, s64, 8, v141
	s_cmp_gt_u32 s1, 7
	s_mov_b64 s[2:3], -1
	v_readlane_b32 s21, v251, 21
	s_cbranch_scc0 .LBB0_261
	s_mov_b64 s[2:3], 0
	s_cmp_lt_i32 s47, 4
	s_mov_b32 s1, s47
	s_cbranch_scc1 .LBB0_260
	s_add_i32 s1, s47, -12
	s_cmp_lt_u32 s1, 4
	s_mov_b64 s[2:3], 0x30c0000
	s_cbranch_scc1 .LBB0_259
	s_lshr_b32 s1, s1, 2
	s_add_i32 s2, s1, 2
	s_cmp_lg_u32 s1, 1
	s_cselect_b32 s1, s2, 1
	s_mul_hi_u32 s3, s1, 0x1040000
	s_mul_i32 s2, s1, 0x1040000

.LBB0_299:
	v_bfe_i32 v3, v16, 27, 1
	v_lshlrev_b32_e32 v2, 4, v16
	v_lshrrev_b32_e32 v3, 22, v3
	v_add_u32_e32 v3, v2, v3
	v_and_b32_e32 v3, 0xfffffc00, v3
	v_sub_u32_e32 v3, v2, v3
	v_ashrrev_i32_e32 v0, 31, v16
	v_lshrrev_b32_e32 v4, 4, v3
	v_lshrrev_b32_e32 v0, 26, v0
	v_bitop3_b32 v3, v4, v3, 32 bitop3:0x6c
	v_add_u32_e32 v0, v16, v0
	v_ashrrev_i32_e32 v5, 31, v3
	v_ashrrev_i32_e32 v0, 6, v0
	v_lshrrev_b32_e32 v5, 26, v5
	v_lshlrev_b32_e32 v4, 3, v0
	v_add_u32_e32 v5, v3, v5
	s_ashr_i32 s42, s35, 2
	s_and_b32 s65, s35, 3
	v_and_b32_e32 v4, -16, v4
	v_ashrrev_i32_e32 v6, 6, v5
	s_add_u32 s38, s62, s0
	v_add_u32_e32 v4, v6, v4
	v_and_b32_e32 v5, 0xc0, v5
	s_addc_u32 s40, s63, s1
	v_sub_u32_e32 v3, v3, v5
	v_lshlrev_b32_e32 v5, 1, v4
	v_lshrrev_b32_e32 v7, 2, v4
	v_and_b32_e32 v6, 3, v6
	s_mov_b32 s1, 0x7fffffe0
	v_lshlrev_b32_e32 v0, 5, v0
	v_ashrrev_i16_sdwa v3, v243, sext(v3) dst_sel:DWORD dst_unused:UNUSED_PAD src0_sel:DWORD src1_sel:BYTE_0
	v_and_b32_e32 v5, 24, v5
	v_and_b32_e32 v7, 4, v7
	v_and_or_b32 v6, v4, s1, v6
	v_and_b32_e32 v0, 32, v0
	v_bfe_i32 v14, v3, 0, 16
	v_or3_b32 v5, v6, v7, v5
	v_add_u32_e32 v3, v0, v14
	v_mul_lo_u32 v15, v4, s29
	v_mul_lo_u32 v4, v5, s29
	v_add_u32_e32 v2, 0x2000, v2
	v_add_lshl_u32 v144, v3, v15, 1
	v_add_lshl_u32 v146, v4, v3, 1
	v_ashrrev_i32_e32 v3, 31, v2
	v_lshrrev_b32_e32 v3, 22, v3
	v_add_u32_e32 v3, v2, v3
	v_ashrrev_i32_e32 v3, 10, v3
	v_mul_i32_i24_e32 v4, 0x400, v3
	v_sub_u32_e32 v2, v2, v4
	v_lshrrev_b32_e32 v4, 4, v2
	v_bitop3_b32 v2, v4, v2, 32 bitop3:0x6c
	v_ashrrev_i32_e32 v5, 31, v2
	v_lshrrev_b32_e32 v5, 26, v5
	v_lshlrev_b32_e32 v4, 3, v3
	v_add_u32_e32 v5, v2, v5
	v_and_b32_e32 v4, -16, v4
	v_ashrrev_i32_e32 v6, 6, v5
	v_add_u32_e32 v4, v6, v4
	v_and_b32_e32 v6, 3, v6
	v_and_or_b32 v6, v4, s1, v6
	s_ashr_i32 s1, s37, 6
	s_ashr_i32 s0, s37, 8
	s_lshl_b32 s96, s29, 8
	s_lshl_b32 s35, s29, 9
	s_lshl_b32 s41, s1, 10
	s_ashr_i32 s43, s42, 31
	s_mul_i32 s21, s42, 0x2080000
	v_lshlrev_b32_e32 v3, 5, v3
	s_mul_hi_i32 s20, s42, 0x2080000
	s_add_u32 s21, s30, s21
	v_and_b32_e32 v17, 32, v3
	v_and_b32_e32 v3, 0xc0, v5
	s_addc_u32 s20, s31, s20
	s_mul_i32 s23, s35, s39
	v_sub_u32_e32 v2, v2, v3
	v_lshlrev_b32_e32 v3, 1, v4
	v_lshrrev_b32_e32 v5, 2, v4
	s_mul_hi_i32 s22, s35, s39
	s_add_u32 s23, s21, s23
	v_and_b32_e32 v3, 24, v3
	v_and_b32_e32 v5, 4, v5
	s_addc_u32 s22, s20, s22
	s_lshl_b64 s[20:21], s[42:43], 21
	v_or3_b32 v3, v6, v5, v3
	s_add_u32 s20, s38, s20
	v_mul_lo_u32 v19, v4, s29
	v_mul_lo_u32 v3, v3, s29
	s_addc_u32 s21, s40, s21
	s_mul_i32 s29, s35, s65
	s_add_u32 s20, s20, s29
	s_addc_u32 s21, s21, 0
	v_writelane_b32 v255, s98, 6
	s_add_u32 s98, s20, s2
	v_ashrrev_i16_sdwa v2, v243, sext(v2) dst_sel:DWORD dst_unused:UNUSED_PAD src0_sel:DWORD src1_sel:BYTE_0
	s_addc_u32 s99, s21, s3
	s_add_i32 s43, s41, 0
	v_bfe_i32 v18, v2, 0, 16
	s_add_i32 m0, s43, 0x10000
	v_add_u32_e32 v2, v17, v18
	global_load_lds_dwordx4 v146, s[98:99]
	s_add_i32 m0, s43, 0x12000
	v_add_lshl_u32 v150, v3, v2, 1
	s_add_u32 s2, s23, s2
	global_load_lds_dwordx4 v150, s[98:99]
	s_addc_u32 s3, s22, s3
	s_mov_b32 m0, s43
	s_add_i32 s44, s43, 0x2000
	v_add_lshl_u32 v148, v2, v19, 1
	global_load_lds_dwordx4 v144, s[2:3]
	s_mov_b32 m0, s44
	s_add_u32 s20, s98, s96
	global_load_lds_dwordx4 v148, s[2:3]
	s_addc_u32 s21, s99, 0
	s_add_i32 m0, s43, 0x14000
	v_mov_b32_e32 v147, v1
	v_mov_b32_e32 v151, v1
	global_load_lds_dwordx4 v146, s[20:21]
	s_add_i32 m0, s43, 0x16000
	v_lshl_add_u64 v[10:11], s[20:21], 0, v[146:147]
	v_lshl_add_u64 v[12:13], s[20:21], 0, v[150:151]
	global_load_lds_dwordx4 v150, s[20:21]
	s_add_u32 s20, s2, s96
	s_addc_u32 s21, s3, 0
	s_add_i32 s45, s43, 0x4000
	s_mov_b32 s25, s40
	s_mov_b32 m0, s45
	s_add_i32 s40, s43, 0x6000
	global_load_lds_dwordx4 v144, s[20:21]
	s_mov_b32 m0, s40
	v_mov_b32_e32 v145, v1
	global_load_lds_dwordx4 v148, s[20:21]
	v_mov_b32_e32 v149, v1
	v_writelane_b32 v255, s37, 7
	s_mov_b32 s74, s38
	v_lshl_add_u64 v[2:3], s[98:99], 0, v[146:147]
	v_lshl_add_u64 v[4:5], s[98:99], 0, v[150:151]
	v_lshl_add_u64 v[6:7], s[2:3], 0, v[144:145]
	v_lshl_add_u64 v[8:9], s[2:3], 0, v[148:149]
	s_cmp_lg_u32 s0, 1
	s_cbranch_scc1 .LBB0_301
	s_setprio 1
	s_barrier

.LBB0_318:
	s_add_i32 s71, s2, 2
	s_add_u32 s98, vcc_lo, 0x80
	s_addc_u32 s3, vcc_hi, 0
	s_add_i32 s73, 0, 0x10000
	v_add_u32_e32 v0, s73, v143
	ds_read_b128 v[168:171], v0
	ds_read_b128 v[172:175], v0 offset:1024
	ds_read_b128 v[176:179], v0 offset:2048
	ds_read_b128 v[180:183], v0 offset:3072
	s_cmp_eq_u32 s22, s2
	s_cselect_b32 s2, s20, s98
	s_cselect_b32 s3, s21, s3
	s_cselect_b32 s99, s1, s47
	s_cselect_b32 s98, s0, s23
	v_lshl_add_u64 v[130:131], vcc, 0, v[152:153]
	s_add_i32 m0, s43, 0xc000
	ds_read_b128 v[184:187], v159
	ds_read_b128 v[188:191], v159 offset:1024
	ds_read_b128 v[192:195], v159 offset:2048
	ds_read_b128 v[196:199], v159 offset:3072
	ds_read_b128 v[200:203], v159 offset:4096
	ds_read_b128 v[204:207], v159 offset:5120
	ds_read_b128 v[208:211], v159 offset:6144
	ds_read_b128 v[212:215], v159 offset:7168
	global_load_lds_dwordx4 v[130:131], off
	v_lshl_add_u64 v[130:131], vcc, 0, v[154:155]
	s_add_i32 m0, s43, 0xe000
	s_nop 0
	global_load_lds_dwordx4 v[130:131], off
	s_waitcnt lgkmcnt(8)
	s_barrier
	s_waitcnt lgkmcnt(0)
	v_mfma_f32_16x16x32_bf16 v[126:129], v[168:171], v[184:187], v[126:129]
	v_mfma_f32_16x16x32_bf16 v[122:125], v[176:179], v[184:187], v[122:125]
	v_mfma_f32_16x16x32_bf16 v[118:121], v[168:171], v[192:195], v[118:121]
	v_mfma_f32_16x16x32_bf16 v[110:113], v[176:179], v[192:195], v[110:113]
	v_mfma_f32_16x16x32_bf16 v[102:105], v[168:171], v[200:203], v[102:105]
	v_mfma_f32_16x16x32_bf16 v[94:97], v[176:179], v[200:203], v[94:97]
	v_mfma_f32_16x16x32_bf16 v[86:89], v[168:171], v[208:211], v[86:89]
	v_mfma_f32_16x16x32_bf16 v[78:81], v[176:179], v[208:211], v[78:81]
	v_mfma_f32_16x16x32_bf16 v[126:129], v[172:175], v[188:191], v[126:129]
	v_mfma_f32_16x16x32_bf16 v[122:125], v[180:183], v[188:191], v[122:125]
	v_mfma_f32_16x16x32_bf16 v[118:121], v[172:175], v[196:199], v[118:121]
	v_mfma_f32_16x16x32_bf16 v[110:113], v[180:183], v[196:199], v[110:113]
	v_mfma_f32_16x16x32_bf16 v[102:105], v[172:175], v[204:207], v[102:105]
	v_mfma_f32_16x16x32_bf16 v[94:97], v[180:183], v[204:207], v[94:97]
	v_mfma_f32_16x16x32_bf16 v[86:89], v[172:175], v[212:215], v[86:89]
	v_mfma_f32_16x16x32_bf16 v[78:81], v[180:183], v[212:215], v[78:81]
	s_barrier
	s_add_i32 s70, 0, 0x14000
	s_add_i32 s73, s73, s41
	v_add_u32_e32 v0, s70, v143
	v_lshl_add_u64 v[130:131], s[98:99], 0, v[146:147]
	s_mov_b32 m0, s73
	ds_read_b128 v[216:219], v0
	ds_read_b128 v[220:223], v0 offset:1024
	ds_read_b128 v[224:227], v0 offset:2048
	ds_read_b128 v[228:231], v0 offset:3072
	global_load_lds_dwordx4 v[130:131], off
	v_lshl_add_u64 v[132:133], s[98:99], 0, v[150:151]
	s_add_i32 m0, s73, 0x2000
	s_nop 0
	global_load_lds_dwordx4 v[132:133], off
	s_barrier
	s_waitcnt lgkmcnt(0)
	v_mfma_f32_16x16x32_bf16 v[114:117], v[216:219], v[184:187], v[114:117]
	v_mfma_f32_16x16x32_bf16 v[106:109], v[224:227], v[184:187], v[106:109]
	v_mfma_f32_16x16x32_bf16 v[98:101], v[216:219], v[192:195], v[98:101]
	v_mfma_f32_16x16x32_bf16 v[90:93], v[224:227], v[192:195], v[90:93]
	v_mfma_f32_16x16x32_bf16 v[82:85], v[216:219], v[200:203], v[82:85]
	v_mfma_f32_16x16x32_bf16 v[74:77], v[224:227], v[200:203], v[74:77]
	v_mfma_f32_16x16x32_bf16 v[70:73], v[216:219], v[208:211], v[70:73]
	v_mfma_f32_16x16x32_bf16 v[66:69], v[224:227], v[208:211], v[66:69]
	v_mfma_f32_16x16x32_bf16 v[114:117], v[220:223], v[188:191], v[114:117]
	v_mfma_f32_16x16x32_bf16 v[106:109], v[228:231], v[188:191], v[106:109]
	v_mfma_f32_16x16x32_bf16 v[98:101], v[220:223], v[196:199], v[98:101]
	v_mfma_f32_16x16x32_bf16 v[90:93], v[228:231], v[196:199], v[90:93]
	v_mfma_f32_16x16x32_bf16 v[82:85], v[220:223], v[204:207], v[82:85]
	v_mfma_f32_16x16x32_bf16 v[74:77], v[228:231], v[204:207], v[74:77]
	v_mfma_f32_16x16x32_bf16 v[70:73], v[220:223], v[212:215], v[70:73]
	v_mfma_f32_16x16x32_bf16 v[66:69], v[228:231], v[212:215], v[66:69]
	s_mov_b32 m0, s43
	v_lshl_add_u64 v[156:157], s[2:3], 0, v[144:145]
	s_barrier
	ds_read_b128 v[184:187], v159 offset:16384
	ds_read_b128 v[188:191], v159 offset:17408
	ds_read_b128 v[192:195], v159 offset:18432
	ds_read_b128 v[196:199], v159 offset:19456
	ds_read_b128 v[200:203], v159 offset:20480
	ds_read_b128 v[204:207], v159 offset:21504
	ds_read_b128 v[208:211], v159 offset:22528
	ds_read_b128 v[212:215], v159 offset:23552
	global_load_lds_dwordx4 v[156:157], off
	v_lshl_add_u64 v[162:163], s[2:3], 0, v[148:149]
	s_mov_b32 m0, s44
	s_nop 0
	global_load_lds_dwordx4 v[162:163], off
	s_barrier
	s_waitcnt lgkmcnt(0)
	v_mfma_f32_16x16x32_bf16 v[62:65], v[168:171], v[184:187], v[62:65]
	v_mfma_f32_16x16x32_bf16 v[58:61], v[176:179], v[184:187], v[58:61]
	v_mfma_f32_16x16x32_bf16 v[54:57], v[168:171], v[192:195], v[54:57]
	v_mfma_f32_16x16x32_bf16 v[46:49], v[176:179], v[192:195], v[46:49]
	v_mfma_f32_16x16x32_bf16 v[38:41], v[168:171], v[200:203], v[38:41]
	v_mfma_f32_16x16x32_bf16 v[30:33], v[176:179], v[200:203], v[30:33]
	v_mfma_f32_16x16x32_bf16 v[22:25], v[168:171], v[208:211], v[22:25]
	v_mfma_f32_16x16x32_bf16 v[14:17], v[176:179], v[208:211], v[14:17]
	v_mfma_f32_16x16x32_bf16 v[62:65], v[172:175], v[188:191], v[62:65]
	v_mfma_f32_16x16x32_bf16 v[58:61], v[180:183], v[188:191], v[58:61]
	v_mfma_f32_16x16x32_bf16 v[54:57], v[172:175], v[196:199], v[54:57]
	v_mfma_f32_16x16x32_bf16 v[46:49], v[180:183], v[196:199], v[46:49]
	v_mfma_f32_16x16x32_bf16 v[38:41], v[172:175], v[204:207], v[38:41]
	v_mfma_f32_16x16x32_bf16 v[30:33], v[180:183], v[204:207], v[30:33]
	v_mfma_f32_16x16x32_bf16 v[22:25], v[172:175], v[212:215], v[22:25]
	v_mfma_f32_16x16x32_bf16 v[14:17], v[180:183], v[212:215], v[14:17]
	s_barrier
	s_add_u32 s98, s98, s96
	s_addc_u32 s99, s99, 0
	s_add_i32 s70, s70, s41
	v_lshl_add_u64 v[164:165], s[98:99], 0, v[146:147]
	s_mov_b32 m0, s70
	v_lshl_add_u64 v[232:233], s[98:99], 0, v[150:151]
	global_load_lds_dwordx4 v[164:165], off
	s_add_i32 m0, s70, 0x2000
	s_nop 0
	global_load_lds_dwordx4 v[232:233], off
	s_waitcnt vmcnt(6)
	s_barrier
	v_mfma_f32_16x16x32_bf16 v[50:53], v[216:219], v[184:187], v[50:53]
	v_mfma_f32_16x16x32_bf16 v[42:45], v[224:227], v[184:187], v[42:45]
	v_mfma_f32_16x16x32_bf16 v[34:37], v[216:219], v[192:195], v[34:37]
	v_mfma_f32_16x16x32_bf16 v[26:29], v[224:227], v[192:195], v[26:29]
	v_mfma_f32_16x16x32_bf16 v[18:21], v[216:219], v[200:203], v[18:21]
	v_mfma_f32_16x16x32_bf16 v[10:13], v[224:227], v[200:203], v[10:13]
	v_mfma_f32_16x16x32_bf16 v[6:9], v[216:219], v[208:211], v[6:9]
	v_mfma_f32_16x16x32_bf16 v[2:5], v[224:227], v[208:211], v[2:5]
	v_mfma_f32_16x16x32_bf16 v[50:53], v[220:223], v[188:191], v[50:53]
	v_mfma_f32_16x16x32_bf16 v[42:45], v[228:231], v[188:191], v[42:45]
	v_mfma_f32_16x16x32_bf16 v[34:37], v[220:223], v[196:199], v[34:37]
	v_mfma_f32_16x16x32_bf16 v[26:29], v[228:231], v[196:199], v[26:29]
	v_mfma_f32_16x16x32_bf16 v[18:21], v[220:223], v[204:207], v[18:21]
	v_mfma_f32_16x16x32_bf16 v[10:13], v[228:231], v[204:207], v[10:13]
	v_mfma_f32_16x16x32_bf16 v[6:9], v[220:223], v[212:215], v[6:9]
	v_mfma_f32_16x16x32_bf16 v[2:5], v[228:231], v[212:215], v[2:5]
	s_add_i32 s70, 0, 0x18000
	v_add_u32_e32 v0, s70, v143
	s_barrier
	ds_read_b128 v[168:171], v0
	ds_read_b128 v[172:175], v0 offset:1024
	ds_read_b128 v[176:179], v0 offset:2048
	ds_read_b128 v[180:183], v0 offset:3072
	s_add_u32 s2, s2, s96
	s_addc_u32 s3, s3, 0
	s_mov_b32 m0, s45
	v_lshl_add_u64 v[216:217], s[2:3], 0, v[144:145]
	ds_read_b128 v[184:187], v159 offset:32768
	ds_read_b128 v[188:191], v159 offset:33792
	ds_read_b128 v[192:195], v159 offset:34816
	ds_read_b128 v[196:199], v159 offset:35840
	ds_read_b128 v[200:203], v159 offset:36864
	ds_read_b128 v[204:207], v159 offset:37888
	ds_read_b128 v[208:211], v159 offset:38912
	ds_read_b128 v[212:215], v159 offset:39936
	global_load_lds_dwordx4 v[216:217], off
	v_lshl_add_u64 v[216:217], s[2:3], 0, v[148:149]
	s_mov_b32 m0, s40
	s_nop 0
	global_load_lds_dwordx4 v[216:217], off
	s_waitcnt lgkmcnt(8)
	s_barrier
	s_waitcnt lgkmcnt(0)
	v_mfma_f32_16x16x32_bf16 v[126:129], v[168:171], v[184:187], v[126:129]
	v_mfma_f32_16x16x32_bf16 v[122:125], v[176:179], v[184:187], v[122:125]
	v_mfma_f32_16x16x32_bf16 v[118:121], v[168:171], v[192:195], v[118:121]
	v_mfma_f32_16x16x32_bf16 v[110:113], v[176:179], v[192:195], v[110:113]
	v_mfma_f32_16x16x32_bf16 v[102:105], v[168:171], v[200:203], v[102:105]
	v_mfma_f32_16x16x32_bf16 v[94:97], v[176:179], v[200:203], v[94:97]
	v_mfma_f32_16x16x32_bf16 v[86:89], v[168:171], v[208:211], v[86:89]
	v_mfma_f32_16x16x32_bf16 v[78:81], v[176:179], v[208:211], v[78:81]
	v_mfma_f32_16x16x32_bf16 v[126:129], v[172:175], v[188:191], v[126:129]
	v_mfma_f32_16x16x32_bf16 v[122:125], v[180:183], v[188:191], v[122:125]
	v_mfma_f32_16x16x32_bf16 v[118:121], v[172:175], v[196:199], v[118:121]
	v_mfma_f32_16x16x32_bf16 v[110:113], v[180:183], v[196:199], v[110:113]
	v_mfma_f32_16x16x32_bf16 v[102:105], v[172:175], v[204:207], v[102:105]
	v_mfma_f32_16x16x32_bf16 v[94:97], v[180:183], v[204:207], v[94:97]
	v_mfma_f32_16x16x32_bf16 v[86:89], v[172:175], v[212:215], v[86:89]
	v_mfma_f32_16x16x32_bf16 v[78:81], v[180:183], v[212:215], v[78:81]
	s_barrier
	s_add_i32 s2, 0, 0x1c000
	s_add_i32 s3, s70, s41
	v_add_u32_e32 v0, s2, v143
	v_lshl_add_u64 v[130:131], v[130:131], 0, s[26:27]
	s_mov_b32 m0, s3
	ds_read_b128 v[216:219], v0
	ds_read_b128 v[220:223], v0 offset:1024
	ds_read_b128 v[224:227], v0 offset:2048
	ds_read_b128 v[228:231], v0 offset:3072
	global_load_lds_dwordx4 v[130:131], off
	v_lshl_add_u64 v[130:131], v[132:133], 0, s[26:27]
	s_add_i32 m0, s3, 0x2000
	s_nop 0
	global_load_lds_dwordx4 v[130:131], off
	s_barrier
	s_waitcnt lgkmcnt(0)
	v_mfma_f32_16x16x32_bf16 v[114:117], v[216:219], v[184:187], v[114:117]
	v_mfma_f32_16x16x32_bf16 v[106:109], v[224:227], v[184:187], v[106:109]
	v_mfma_f32_16x16x32_bf16 v[98:101], v[216:219], v[192:195], v[98:101]
	v_mfma_f32_16x16x32_bf16 v[90:93], v[224:227], v[192:195], v[90:93]
	v_mfma_f32_16x16x32_bf16 v[82:85], v[216:219], v[200:203], v[82:85]
	v_mfma_f32_16x16x32_bf16 v[74:77], v[224:227], v[200:203], v[74:77]
	v_mfma_f32_16x16x32_bf16 v[70:73], v[216:219], v[208:211], v[70:73]
	v_mfma_f32_16x16x32_bf16 v[66:69], v[224:227], v[208:211], v[66:69]
	v_mfma_f32_16x16x32_bf16 v[114:117], v[220:223], v[188:191], v[114:117]
	v_mfma_f32_16x16x32_bf16 v[106:109], v[228:231], v[188:191], v[106:109]
	v_mfma_f32_16x16x32_bf16 v[98:101], v[220:223], v[196:199], v[98:101]
	v_mfma_f32_16x16x32_bf16 v[90:93], v[228:231], v[196:199], v[90:93]
	v_mfma_f32_16x16x32_bf16 v[82:85], v[220:223], v[204:207], v[82:85]
	v_mfma_f32_16x16x32_bf16 v[74:77], v[228:231], v[204:207], v[74:77]
	v_mfma_f32_16x16x32_bf16 v[70:73], v[220:223], v[212:215], v[70:73]
	v_mfma_f32_16x16x32_bf16 v[66:69], v[228:231], v[212:215], v[66:69]
	s_mov_b32 m0, s66
	v_lshl_add_u64 v[130:131], v[156:157], 0, s[26:27]
	s_barrier
	ds_read_b128 v[184:187], v159 offset:49152
	ds_read_b128 v[188:191], v159 offset:50176
	ds_read_b128 v[192:195], v159 offset:51200
	ds_read_b128 v[196:199], v159 offset:52224
	ds_read_b128 v[200:203], v159 offset:53248
	ds_read_b128 v[204:207], v159 offset:54272
	ds_read_b128 v[208:211], v159 offset:55296
	ds_read_b128 v[212:215], v159 offset:56320
	global_load_lds_dwordx4 v[130:131], off
	v_lshl_add_u64 v[130:131], v[162:163], 0, s[26:27]
	s_mov_b32 m0, s67
	s_nop 0
	global_load_lds_dwordx4 v[130:131], off
	s_barrier
	s_waitcnt lgkmcnt(0)
	v_mfma_f32_16x16x32_bf16 v[62:65], v[168:171], v[184:187], v[62:65]
	v_mfma_f32_16x16x32_bf16 v[58:61], v[176:179], v[184:187], v[58:61]
	v_mfma_f32_16x16x32_bf16 v[54:57], v[168:171], v[192:195], v[54:57]
	v_mfma_f32_16x16x32_bf16 v[46:49], v[176:179], v[192:195], v[46:49]
	v_mfma_f32_16x16x32_bf16 v[38:41], v[168:171], v[200:203], v[38:41]
	v_mfma_f32_16x16x32_bf16 v[30:33], v[176:179], v[200:203], v[30:33]
	v_mfma_f32_16x16x32_bf16 v[22:25], v[168:171], v[208:211], v[22:25]
	v_mfma_f32_16x16x32_bf16 v[14:17], v[176:179], v[208:211], v[14:17]
	v_mfma_f32_16x16x32_bf16 v[62:65], v[172:175], v[188:191], v[62:65]
	v_mfma_f32_16x16x32_bf16 v[58:61], v[180:183], v[188:191], v[58:61]
	v_mfma_f32_16x16x32_bf16 v[54:57], v[172:175], v[196:199], v[54:57]
	v_mfma_f32_16x16x32_bf16 v[46:49], v[180:183], v[196:199], v[46:49]
	v_mfma_f32_16x16x32_bf16 v[38:41], v[172:175], v[204:207], v[38:41]
	v_mfma_f32_16x16x32_bf16 v[30:33], v[180:183], v[204:207], v[30:33]
	v_mfma_f32_16x16x32_bf16 v[22:25], v[172:175], v[212:215], v[22:25]
	v_mfma_f32_16x16x32_bf16 v[14:17], v[180:183], v[212:215], v[14:17]
	s_barrier
	s_add_i32 s2, s2, s41
	v_lshl_add_u64 v[130:131], v[164:165], 0, s[26:27]
	s_mov_b32 m0, s2
	s_nop 0
	global_load_lds_dwordx4 v[130:131], off
	v_lshl_add_u64 v[130:131], v[232:233], 0, s[26:27]
	s_add_i32 m0, s2, 0x2000
	s_nop 0
	global_load_lds_dwordx4 v[130:131], off
	s_waitcnt vmcnt(6)
	s_barrier
	v_mfma_f32_16x16x32_bf16 v[50:53], v[216:219], v[184:187], v[50:53]
	v_mfma_f32_16x16x32_bf16 v[42:45], v[224:227], v[184:187], v[42:45]
	v_mfma_f32_16x16x32_bf16 v[34:37], v[216:219], v[192:195], v[34:37]
	v_mfma_f32_16x16x32_bf16 v[26:29], v[224:227], v[192:195], v[26:29]
	v_mfma_f32_16x16x32_bf16 v[18:21], v[216:219], v[200:203], v[18:21]
	v_mfma_f32_16x16x32_bf16 v[10:13], v[224:227], v[200:203], v[10:13]
	v_mfma_f32_16x16x32_bf16 v[6:9], v[216:219], v[208:211], v[6:9]
	v_mfma_f32_16x16x32_bf16 v[2:5], v[224:227], v[208:211], v[2:5]
	v_mfma_f32_16x16x32_bf16 v[50:53], v[220:223], v[188:191], v[50:53]
	v_mfma_f32_16x16x32_bf16 v[42:45], v[228:231], v[188:191], v[42:45]
	v_mfma_f32_16x16x32_bf16 v[34:37], v[220:223], v[196:199], v[34:37]
	v_mfma_f32_16x16x32_bf16 v[26:29], v[228:231], v[196:199], v[26:29]
	v_mfma_f32_16x16x32_bf16 v[18:21], v[220:223], v[204:207], v[18:21]
	v_mfma_f32_16x16x32_bf16 v[10:13], v[228:231], v[204:207], v[10:13]
	v_mfma_f32_16x16x32_bf16 v[6:9], v[220:223], v[212:215], v[6:9]
	v_mfma_f32_16x16x32_bf16 v[2:5], v[228:231], v[212:215], v[2:5]
	s_add_u32 vcc_lo, vcc_lo, 0x100
	s_addc_u32 vcc_hi, vcc_hi, 0
	s_add_u32 s23, s23, 0x100
	s_addc_u32 s47, s47, 0
	s_cmp_ge_u32 s71, s68
	s_mov_b32 s2, s71
	s_barrier
	s_cbranch_scc0 .LBB0_318
	s_cmp_gt_i32 s64, -1
	s_cbranch_scc0 .LBB0_321
	v_lshlrev_b32_e64 v0, v158, s64
	v_add_u32_e32 v130, s42, v0
	v_ashrrev_i32_e32 v131, 31, v130
	v_readlane_b32 s2, v255, 12
	v_lshlrev_b64 v[130:131], 19, v[130:131]
	v_readlane_b32 s3, v255, 13
	s_nop 1
	v_lshl_add_u64 v[156:157], s[2:3], 0, v[130:131]
	s_mov_b32 s2, 0
	s_cbranch_execnz .LBB0_303
	s_branch .LBB0_302

.LBB0_424:
	s_and_b64 vcc, exec, s[0:1]
	s_cbranch_vccz .LBB0_503
	v_readlane_b32 s0, v250, 5
	s_waitcnt vmcnt(0)
	v_mov_b32_e32 v2, v160
	v_readlane_b32 s1, v250, 6
	s_andn2_b64 vcc, exec, s[0:1]
	v_readfirstlane_b32 s71, v2
	s_cbranch_vccnz .LBB0_443
	v_lshlrev_b32_e32 v0, 4, v2
	v_add_u32_e32 v4, 0x2000, v0
	v_ashrrev_i32_e32 v3, 31, v4
	v_lshrrev_b32_e32 v3, 22, v3
	v_add_u32_e32 v3, v4, v3
	v_ashrrev_i32_e32 v3, 10, v3
	v_mul_i32_i24_e32 v5, 0x400, v3
	v_sub_u32_e32 v4, v4, v5
	v_lshrrev_b32_e32 v5, 4, v4
	v_bitop3_b32 v5, v5, v4, 32 bitop3:0x6c
	v_ashrrev_i32_e32 v4, 31, v5
	v_lshrrev_b32_e32 v4, 26, v4
	v_add_u32_e32 v6, v5, v4
	v_lshlrev_b32_e32 v7, 3, v3
	v_ashrrev_i32_e32 v4, 6, v6
	v_and_b32_e32 v7, -16, v7
	v_add_u32_e32 v7, v4, v7
	v_and_b32_e32 v8, 3, v4
	s_mov_b32 s1, 0x1fffe0
	v_lshrrev_b32_e32 v9, 2, v7
	v_lshlrev_b32_e32 v10, 1, v7
	v_and_b32_e32 v6, 0xc0, v6
	v_and_or_b32 v8, v7, s1, v8
	v_and_b32_e32 v9, 4, v9
	v_and_b32_e32 v10, 24, v10
	v_sub_u32_e32 v5, v5, v6
	v_or3_b32 v8, v8, v9, v10
	v_lshlrev_b32_e32 v9, 5, v3
	v_ashrrev_i16_sdwa v5, v243, sext(v5) dst_sel:DWORD dst_unused:UNUSED_PAD src0_sel:DWORD src1_sel:BYTE_0
	v_and_b32_e32 v9, 32, v9
	v_bfe_i32 v5, v5, 0, 16
	v_add_lshl_u32 v6, v9, v5, 1
	v_lshl_add_u32 v144, v8, 11, v6
	v_lshl_add_u32 v146, v7, 11, v6
	v_bfe_i32 v6, v2, 27, 1
	v_lshrrev_b32_e32 v6, 22, v6
	v_add_u32_e32 v6, v0, v6
	v_and_b32_e32 v6, 0xfffffc00, v6
	v_sub_u32_e32 v0, v0, v6
	v_lshrrev_b32_e32 v6, 4, v0
	v_ashrrev_i32_e32 v7, 31, v2
	v_bitop3_b32 v0, v6, v0, 32 bitop3:0x6c
	v_lshrrev_b32_e32 v7, 26, v7
	v_ashrrev_i32_e32 v6, 31, v0
	v_add_u32_e32 v7, v2, v7
	v_lshrrev_b32_e32 v6, 26, v6
	v_ashrrev_i32_e32 v7, 6, v7
	v_add_u32_e32 v8, v0, v6
	v_lshlrev_b32_e32 v9, 3, v7
	v_ashrrev_i32_e32 v6, 6, v8
	v_and_b32_e32 v9, -16, v9
	v_add_u32_e32 v9, v6, v9
	v_and_b32_e32 v10, 3, v6
	v_lshrrev_b32_e32 v11, 2, v9
	v_lshlrev_b32_e32 v12, 1, v9
	v_and_b32_e32 v8, 0xc0, v8
	v_and_or_b32 v10, v9, s1, v10
	v_and_b32_e32 v11, 4, v11
	v_and_b32_e32 v12, 24, v12
	v_sub_u32_e32 v0, v0, v8
	s_ashr_i32 s0, s71, 6
	v_or3_b32 v10, v10, v11, v12
	v_lshlrev_b32_e32 v11, 5, v7
	v_ashrrev_i16_sdwa v0, v243, sext(v0) dst_sel:DWORD dst_unused:UNUSED_PAD src0_sel:DWORD src1_sel:BYTE_0
	s_mov_b32 s30, s98
	s_lshl_b32 s98, s0, 10
	v_and_b32_e32 v11, 32, v11
	v_bfe_i32 v8, v0, 0, 16
	v_add_lshl_u32 v11, v11, v8, 1
	s_add_i32 s99, s98, 0
	v_readlane_b32 s2, v253, 39
	v_lshl_add_u32 v0, v10, 11, v11
	s_add_i32 m0, s99, 0x10000
	v_readlane_b32 s3, v253, 40
	s_mov_b32 s25, s41
	v_lshl_add_u32 v148, v9, 11, v11
	s_add_i32 s41, s99, 0x2000
	s_add_i32 s96, s99, 0x4000
	s_add_i32 s35, s99, 0x6000
	global_load_lds_dwordx4 v0, s[2:3]
	s_add_i32 m0, s99, 0x12000
	s_nop 0
	global_load_lds_dwordx4 v144, s[2:3]
	v_readlane_b32 s2, v253, 35
	s_mov_b32 m0, s99
	v_readlane_b32 s3, v253, 36
	s_nop 4
	global_load_lds_dwordx4 v148, s[2:3]
	s_mov_b32 m0, s41
	s_nop 0
	global_load_lds_dwordx4 v146, s[2:3]
	v_readlane_b32 s2, v253, 33
	s_add_i32 m0, s99, 0x14000
	v_readlane_b32 s3, v253, 34
	s_nop 4
	global_load_lds_dwordx4 v0, s[2:3]
	s_add_i32 m0, s99, 0x16000
	s_nop 0
	global_load_lds_dwordx4 v144, s[2:3]
	v_readlane_b32 s2, v253, 37
	s_mov_b32 m0, s96
	v_readlane_b32 s3, v253, 38
	s_nop 4
	global_load_lds_dwordx4 v148, s[2:3]
	s_mov_b32 m0, s35
	s_nop 0
	global_load_lds_dwordx4 v146, s[2:3]
	s_ashr_i32 s2, s71, 8
	s_cmp_lg_u32 s2, 1
	s_cbranch_scc1 .LBB0_428
	s_setprio 1
	s_barrier

.LBB0_437:
	s_add_u32 s2, s20, 0xfffc0080
	s_addc_u32 s3, s21, -1
	s_add_i32 s68, 0, 0x10000
	v_add_u32_e32 v130, s68, v143
	ds_read_b128 v[168:171], v130
	ds_read_b128 v[172:175], v130 offset:1024
	ds_read_b128 v[176:179], v130 offset:2048
	ds_read_b128 v[180:183], v130 offset:3072
	s_cmp_eq_u32 s67, 12
	s_cselect_b32 s29, s22, s3
	s_cselect_b32 s28, s23, s2
	s_cselect_b32 s3, s37, s66
	s_cselect_b32 s2, s43, s65
	v_lshl_add_u64 v[130:131], s[20:21], 0, v[150:151]
	s_add_i32 m0, s99, 0xc000
	ds_read_b128 v[184:187], v157
	ds_read_b128 v[188:191], v157 offset:1024
	ds_read_b128 v[192:195], v157 offset:2048
	ds_read_b128 v[196:199], v157 offset:3072
	ds_read_b128 v[200:203], v157 offset:4096
	ds_read_b128 v[204:207], v157 offset:5120
	ds_read_b128 v[208:211], v157 offset:6144
	ds_read_b128 v[212:215], v157 offset:7168
	global_load_lds_dwordx4 v[130:131], off
	v_lshl_add_u64 v[130:131], s[20:21], 0, v[152:153]
	s_add_i32 m0, s99, 0xe000
	s_nop 0
	global_load_lds_dwordx4 v[130:131], off
	s_waitcnt lgkmcnt(8)
	s_barrier
	s_waitcnt lgkmcnt(0)
	v_mfma_f32_16x16x32_bf16 v[126:129], v[168:171], v[184:187], v[126:129]
	v_mfma_f32_16x16x32_bf16 v[114:117], v[176:179], v[184:187], v[114:117]
	v_mfma_f32_16x16x32_bf16 v[110:113], v[168:171], v[192:195], v[110:113]
	v_mfma_f32_16x16x32_bf16 v[98:101], v[176:179], v[192:195], v[98:101]
	v_mfma_f32_16x16x32_bf16 v[94:97], v[168:171], v[200:203], v[94:97]
	v_mfma_f32_16x16x32_bf16 v[82:85], v[176:179], v[200:203], v[82:85]
	v_mfma_f32_16x16x32_bf16 v[78:81], v[168:171], v[208:211], v[78:81]
	v_mfma_f32_16x16x32_bf16 v[66:69], v[176:179], v[208:211], v[66:69]
	v_mfma_f32_16x16x32_bf16 v[126:129], v[172:175], v[188:191], v[126:129]
	v_mfma_f32_16x16x32_bf16 v[114:117], v[180:183], v[188:191], v[114:117]
	v_mfma_f32_16x16x32_bf16 v[110:113], v[172:175], v[196:199], v[110:113]
	v_mfma_f32_16x16x32_bf16 v[98:101], v[180:183], v[196:199], v[98:101]
	v_mfma_f32_16x16x32_bf16 v[94:97], v[172:175], v[204:207], v[94:97]
	v_mfma_f32_16x16x32_bf16 v[82:85], v[180:183], v[204:207], v[82:85]
	v_mfma_f32_16x16x32_bf16 v[78:81], v[172:175], v[212:215], v[78:81]
	v_mfma_f32_16x16x32_bf16 v[66:69], v[180:183], v[212:215], v[66:69]
	s_barrier
	s_add_i32 s70, 0, 0x14000
	v_add_u32_e32 v130, s70, v143
	s_add_i32 s68, s68, s98
	ds_read_b128 v[216:219], v130
	ds_read_b128 v[220:223], v130 offset:1024
	ds_read_b128 v[224:227], v130 offset:2048
	ds_read_b128 v[228:231], v130 offset:3072
	v_lshl_add_u64 v[130:131], s[2:3], 0, v[0:1]
	s_mov_b32 m0, s68
	v_lshl_add_u64 v[132:133], s[2:3], 0, v[144:145]
	global_load_lds_dwordx4 v[130:131], off
	s_add_i32 m0, s68, 0x2000
	s_nop 0
	global_load_lds_dwordx4 v[132:133], off
	s_barrier
	s_waitcnt lgkmcnt(0)
	v_mfma_f32_16x16x32_bf16 v[122:125], v[216:219], v[184:187], v[122:125]
	v_mfma_f32_16x16x32_bf16 v[118:121], v[224:227], v[184:187], v[118:121]
	v_mfma_f32_16x16x32_bf16 v[106:109], v[216:219], v[192:195], v[106:109]
	v_mfma_f32_16x16x32_bf16 v[102:105], v[224:227], v[192:195], v[102:105]
	v_mfma_f32_16x16x32_bf16 v[90:93], v[216:219], v[200:203], v[90:93]
	v_mfma_f32_16x16x32_bf16 v[86:89], v[224:227], v[200:203], v[86:89]
	v_mfma_f32_16x16x32_bf16 v[74:77], v[216:219], v[208:211], v[74:77]
	v_mfma_f32_16x16x32_bf16 v[70:73], v[224:227], v[208:211], v[70:73]
	v_mfma_f32_16x16x32_bf16 v[122:125], v[220:223], v[188:191], v[122:125]
	v_mfma_f32_16x16x32_bf16 v[118:121], v[228:231], v[188:191], v[118:121]
	v_mfma_f32_16x16x32_bf16 v[106:109], v[220:223], v[196:199], v[106:109]
	v_mfma_f32_16x16x32_bf16 v[102:105], v[228:231], v[196:199], v[102:105]
	v_mfma_f32_16x16x32_bf16 v[90:93], v[220:223], v[204:207], v[90:93]
	v_mfma_f32_16x16x32_bf16 v[86:89], v[228:231], v[204:207], v[86:89]
	v_mfma_f32_16x16x32_bf16 v[74:77], v[220:223], v[212:215], v[74:77]
	v_mfma_f32_16x16x32_bf16 v[70:73], v[228:231], v[212:215], v[70:73]
	s_mov_b32 m0, s99
	v_lshl_add_u64 v[154:155], s[28:29], 0, v[148:149]
	s_barrier
	ds_read_b128 v[184:187], v157 offset:16384
	ds_read_b128 v[188:191], v157 offset:17408
	ds_read_b128 v[192:195], v157 offset:18432
	ds_read_b128 v[196:199], v157 offset:19456
	ds_read_b128 v[200:203], v157 offset:20480
	ds_read_b128 v[204:207], v157 offset:21504
	ds_read_b128 v[208:211], v157 offset:22528
	ds_read_b128 v[212:215], v157 offset:23552
	global_load_lds_dwordx4 v[154:155], off
	v_lshl_add_u64 v[158:159], s[28:29], 0, v[146:147]
	s_mov_b32 m0, s41
	s_nop 0
	global_load_lds_dwordx4 v[158:159], off
	s_barrier
	s_waitcnt lgkmcnt(0)
	v_mfma_f32_16x16x32_bf16 v[62:65], v[168:171], v[184:187], v[62:65]
	v_mfma_f32_16x16x32_bf16 v[50:53], v[176:179], v[184:187], v[50:53]
	v_mfma_f32_16x16x32_bf16 v[46:49], v[168:171], v[192:195], v[46:49]
	v_mfma_f32_16x16x32_bf16 v[34:37], v[176:179], v[192:195], v[34:37]
	v_mfma_f32_16x16x32_bf16 v[30:33], v[168:171], v[200:203], v[30:33]
	v_mfma_f32_16x16x32_bf16 v[18:21], v[176:179], v[200:203], v[18:21]
	v_mfma_f32_16x16x32_bf16 v[14:17], v[168:171], v[208:211], v[14:17]
	v_mfma_f32_16x16x32_bf16 v[6:9], v[176:179], v[208:211], v[6:9]
	v_mfma_f32_16x16x32_bf16 v[62:65], v[172:175], v[188:191], v[62:65]
	v_mfma_f32_16x16x32_bf16 v[50:53], v[180:183], v[188:191], v[50:53]
	v_mfma_f32_16x16x32_bf16 v[46:49], v[172:175], v[196:199], v[46:49]
	v_mfma_f32_16x16x32_bf16 v[34:37], v[180:183], v[196:199], v[34:37]
	v_mfma_f32_16x16x32_bf16 v[30:33], v[172:175], v[204:207], v[30:33]
	v_mfma_f32_16x16x32_bf16 v[18:21], v[180:183], v[204:207], v[18:21]
	v_mfma_f32_16x16x32_bf16 v[14:17], v[172:175], v[212:215], v[14:17]
	v_mfma_f32_16x16x32_bf16 v[6:9], v[180:183], v[212:215], v[6:9]
	s_barrier
	s_add_u32 s68, s2, 0x40000
	s_addc_u32 s69, s3, 0
	s_add_i32 s70, s70, s98
	v_lshl_add_u64 v[162:163], s[68:69], 0, v[0:1]
	s_mov_b32 m0, s70
	s_nop 0
	global_load_lds_dwordx4 v[162:163], off
	v_lshl_add_u64 v[162:163], s[68:69], 0, v[144:145]
	s_add_i32 m0, s70, 0x2000
	s_nop 0
	global_load_lds_dwordx4 v[162:163], off
	s_waitcnt vmcnt(6)
	s_barrier
	v_mfma_f32_16x16x32_bf16 v[58:61], v[216:219], v[184:187], v[58:61]
	v_mfma_f32_16x16x32_bf16 v[54:57], v[224:227], v[184:187], v[54:57]
	v_mfma_f32_16x16x32_bf16 v[42:45], v[216:219], v[192:195], v[42:45]
	v_mfma_f32_16x16x32_bf16 v[38:41], v[224:227], v[192:195], v[38:41]
	v_mfma_f32_16x16x32_bf16 v[26:29], v[216:219], v[200:203], v[26:29]
	v_mfma_f32_16x16x32_bf16 v[22:25], v[224:227], v[200:203], v[22:25]
	v_mfma_f32_16x16x32_bf16 v[10:13], v[216:219], v[208:211], v[10:13]
	v_mfma_f32_16x16x32_bf16 v[2:5], v[224:227], v[208:211], v[2:5]
	v_mfma_f32_16x16x32_bf16 v[58:61], v[220:223], v[188:191], v[58:61]
	v_mfma_f32_16x16x32_bf16 v[54:57], v[228:231], v[188:191], v[54:57]
	v_mfma_f32_16x16x32_bf16 v[42:45], v[220:223], v[196:199], v[42:45]
	v_mfma_f32_16x16x32_bf16 v[38:41], v[228:231], v[196:199], v[38:41]
	v_mfma_f32_16x16x32_bf16 v[26:29], v[220:223], v[204:207], v[26:29]
	v_mfma_f32_16x16x32_bf16 v[22:25], v[228:231], v[204:207], v[22:25]
	v_mfma_f32_16x16x32_bf16 v[10:13], v[220:223], v[212:215], v[10:13]
	v_mfma_f32_16x16x32_bf16 v[2:5], v[228:231], v[212:215], v[2:5]
	s_add_i32 s68, 0, 0x18000
	v_add_u32_e32 v162, s68, v143
	s_barrier
	ds_read_b128 v[168:171], v162
	ds_read_b128 v[172:175], v162 offset:1024
	ds_read_b128 v[176:179], v162 offset:2048
	ds_read_b128 v[180:183], v162 offset:3072
	s_add_u32 s28, s28, 0x40000
	s_addc_u32 s29, s29, 0
	s_mov_b32 m0, s96
	v_lshl_add_u64 v[162:163], s[28:29], 0, v[148:149]
	ds_read_b128 v[184:187], v157 offset:32768
	ds_read_b128 v[188:191], v157 offset:33792
	ds_read_b128 v[192:195], v157 offset:34816
	ds_read_b128 v[196:199], v157 offset:35840
	ds_read_b128 v[200:203], v157 offset:36864
	ds_read_b128 v[204:207], v157 offset:37888
	ds_read_b128 v[208:211], v157 offset:38912
	ds_read_b128 v[212:215], v157 offset:39936
	global_load_lds_dwordx4 v[162:163], off
	v_lshl_add_u64 v[162:163], s[28:29], 0, v[146:147]
	s_mov_b32 m0, s35
	s_nop 0
	global_load_lds_dwordx4 v[162:163], off
	s_waitcnt lgkmcnt(8)
	s_barrier
	s_waitcnt lgkmcnt(0)
	v_mfma_f32_16x16x32_bf16 v[126:129], v[168:171], v[184:187], v[126:129]
	v_mfma_f32_16x16x32_bf16 v[114:117], v[176:179], v[184:187], v[114:117]
	v_mfma_f32_16x16x32_bf16 v[110:113], v[168:171], v[192:195], v[110:113]
	v_mfma_f32_16x16x32_bf16 v[98:101], v[176:179], v[192:195], v[98:101]
	v_mfma_f32_16x16x32_bf16 v[94:97], v[168:171], v[200:203], v[94:97]
	v_mfma_f32_16x16x32_bf16 v[82:85], v[176:179], v[200:203], v[82:85]
	v_mfma_f32_16x16x32_bf16 v[78:81], v[168:171], v[208:211], v[78:81]
	v_mfma_f32_16x16x32_bf16 v[66:69], v[176:179], v[208:211], v[66:69]
	v_mfma_f32_16x16x32_bf16 v[126:129], v[172:175], v[188:191], v[126:129]
	v_mfma_f32_16x16x32_bf16 v[114:117], v[180:183], v[188:191], v[114:117]
	v_mfma_f32_16x16x32_bf16 v[110:113], v[172:175], v[196:199], v[110:113]
	v_mfma_f32_16x16x32_bf16 v[98:101], v[180:183], v[196:199], v[98:101]
	v_mfma_f32_16x16x32_bf16 v[94:97], v[172:175], v[204:207], v[94:97]
	v_mfma_f32_16x16x32_bf16 v[82:85], v[180:183], v[204:207], v[82:85]
	v_mfma_f32_16x16x32_bf16 v[78:81], v[172:175], v[212:215], v[78:81]
	v_mfma_f32_16x16x32_bf16 v[66:69], v[180:183], v[212:215], v[66:69]
	s_barrier
	s_add_i32 s28, 0, 0x1c000
	s_add_i32 s29, s68, s98
	v_add_u32_e32 v162, s28, v143
	v_lshl_add_u64 v[130:131], v[130:131], 0, s[26:27]
	s_mov_b32 m0, s29
	ds_read_b128 v[216:219], v162
	ds_read_b128 v[220:223], v162 offset:1024
	ds_read_b128 v[224:227], v162 offset:2048
	ds_read_b128 v[228:231], v162 offset:3072
	global_load_lds_dwordx4 v[130:131], off
	v_lshl_add_u64 v[130:131], v[132:133], 0, s[26:27]
	s_add_i32 m0, s29, 0x2000
	s_nop 0
	global_load_lds_dwordx4 v[130:131], off
	s_barrier
	s_waitcnt lgkmcnt(0)
	v_mfma_f32_16x16x32_bf16 v[122:125], v[216:219], v[184:187], v[122:125]
	v_mfma_f32_16x16x32_bf16 v[118:121], v[224:227], v[184:187], v[118:121]
	v_mfma_f32_16x16x32_bf16 v[106:109], v[216:219], v[192:195], v[106:109]
	v_mfma_f32_16x16x32_bf16 v[102:105], v[224:227], v[192:195], v[102:105]
	v_mfma_f32_16x16x32_bf16 v[90:93], v[216:219], v[200:203], v[90:93]
	v_mfma_f32_16x16x32_bf16 v[86:89], v[224:227], v[200:203], v[86:89]
	v_mfma_f32_16x16x32_bf16 v[74:77], v[216:219], v[208:211], v[74:77]
	v_mfma_f32_16x16x32_bf16 v[70:73], v[224:227], v[208:211], v[70:73]
	v_mfma_f32_16x16x32_bf16 v[122:125], v[220:223], v[188:191], v[122:125]
	v_mfma_f32_16x16x32_bf16 v[118:121], v[228:231], v[188:191], v[118:121]
	v_mfma_f32_16x16x32_bf16 v[106:109], v[220:223], v[196:199], v[106:109]
	v_mfma_f32_16x16x32_bf16 v[102:105], v[228:231], v[196:199], v[102:105]
	v_mfma_f32_16x16x32_bf16 v[90:93], v[220:223], v[204:207], v[90:93]
	v_mfma_f32_16x16x32_bf16 v[86:89], v[228:231], v[204:207], v[86:89]
	v_mfma_f32_16x16x32_bf16 v[74:77], v[220:223], v[212:215], v[74:77]
	v_mfma_f32_16x16x32_bf16 v[70:73], v[228:231], v[212:215], v[70:73]
	s_mov_b32 m0, s33
	v_lshl_add_u64 v[130:131], v[154:155], 0, s[26:27]
	s_barrier
	ds_read_b128 v[184:187], v157 offset:49152
	ds_read_b128 v[188:191], v157 offset:50176
	ds_read_b128 v[192:195], v157 offset:51200
	ds_read_b128 v[196:199], v157 offset:52224
	ds_read_b128 v[200:203], v157 offset:53248
	ds_read_b128 v[204:207], v157 offset:54272
	ds_read_b128 v[208:211], v157 offset:55296
	ds_read_b128 v[212:215], v157 offset:56320
	global_load_lds_dwordx4 v[130:131], off
	v_lshl_add_u64 v[130:131], v[158:159], 0, s[26:27]
	s_mov_b32 m0, s44
	s_nop 0
	global_load_lds_dwordx4 v[130:131], off
	s_barrier
	s_waitcnt lgkmcnt(0)
	v_mfma_f32_16x16x32_bf16 v[62:65], v[168:171], v[184:187], v[62:65]
	v_mfma_f32_16x16x32_bf16 v[50:53], v[176:179], v[184:187], v[50:53]
	v_mfma_f32_16x16x32_bf16 v[46:49], v[168:171], v[192:195], v[46:49]
	v_mfma_f32_16x16x32_bf16 v[34:37], v[176:179], v[192:195], v[34:37]
	v_mfma_f32_16x16x32_bf16 v[30:33], v[168:171], v[200:203], v[30:33]
	v_mfma_f32_16x16x32_bf16 v[18:21], v[176:179], v[200:203], v[18:21]
	v_mfma_f32_16x16x32_bf16 v[14:17], v[168:171], v[208:211], v[14:17]
	v_mfma_f32_16x16x32_bf16 v[6:9], v[176:179], v[208:211], v[6:9]
	v_mfma_f32_16x16x32_bf16 v[62:65], v[172:175], v[188:191], v[62:65]
	v_mfma_f32_16x16x32_bf16 v[50:53], v[180:183], v[188:191], v[50:53]
	v_mfma_f32_16x16x32_bf16 v[46:49], v[172:175], v[196:199], v[46:49]
	v_mfma_f32_16x16x32_bf16 v[34:37], v[180:183], v[196:199], v[34:37]
	v_mfma_f32_16x16x32_bf16 v[30:33], v[172:175], v[204:207], v[30:33]
	v_mfma_f32_16x16x32_bf16 v[18:21], v[180:183], v[204:207], v[18:21]
	v_mfma_f32_16x16x32_bf16 v[14:17], v[172:175], v[212:215], v[14:17]
	v_mfma_f32_16x16x32_bf16 v[6:9], v[180:183], v[212:215], v[6:9]
	s_barrier
	s_add_u32 s2, s2, 0x40080
	s_addc_u32 s3, s3, 0
	s_add_i32 s28, s28, s98
	v_lshl_add_u64 v[130:131], s[2:3], 0, v[0:1]
	s_mov_b32 m0, s28
	s_nop 0
	global_load_lds_dwordx4 v[130:131], off
	v_lshl_add_u64 v[130:131], s[2:3], 0, v[144:145]
	s_add_i32 m0, s28, 0x2000
	s_nop 0
	global_load_lds_dwordx4 v[130:131], off
	s_waitcnt vmcnt(6)
	s_barrier
	v_mfma_f32_16x16x32_bf16 v[58:61], v[216:219], v[184:187], v[58:61]
	v_mfma_f32_16x16x32_bf16 v[54:57], v[224:227], v[184:187], v[54:57]
	v_mfma_f32_16x16x32_bf16 v[42:45], v[216:219], v[192:195], v[42:45]
	v_mfma_f32_16x16x32_bf16 v[38:41], v[224:227], v[192:195], v[38:41]
	v_mfma_f32_16x16x32_bf16 v[26:29], v[216:219], v[200:203], v[26:29]
	v_mfma_f32_16x16x32_bf16 v[22:25], v[224:227], v[200:203], v[22:25]
	v_mfma_f32_16x16x32_bf16 v[10:13], v[216:219], v[208:211], v[10:13]
	v_mfma_f32_16x16x32_bf16 v[2:5], v[224:227], v[208:211], v[2:5]
	v_mfma_f32_16x16x32_bf16 v[58:61], v[220:223], v[188:191], v[58:61]
	v_mfma_f32_16x16x32_bf16 v[54:57], v[228:231], v[188:191], v[54:57]
	v_mfma_f32_16x16x32_bf16 v[42:45], v[220:223], v[196:199], v[42:45]
	v_mfma_f32_16x16x32_bf16 v[38:41], v[228:231], v[196:199], v[38:41]
	v_mfma_f32_16x16x32_bf16 v[26:29], v[220:223], v[204:207], v[26:29]
	v_mfma_f32_16x16x32_bf16 v[22:25], v[228:231], v[204:207], v[22:25]
	v_mfma_f32_16x16x32_bf16 v[10:13], v[220:223], v[212:215], v[10:13]
	v_mfma_f32_16x16x32_bf16 v[2:5], v[228:231], v[212:215], v[2:5]
	s_add_i32 s67, s67, 2
	s_add_u32 s20, s20, 0x100
	s_addc_u32 s21, s21, 0
	s_add_u32 s65, s65, 0x100
	s_addc_u32 s66, s66, 0
	s_cmp_gt_u32 s67, 13
	s_barrier
	s_cbranch_scc0 .LBB0_437
	s_andn2_b64 vcc, exec, s[0:1]
	s_cbranch_vccnz .LBB0_429
	v_pk_mul_f32 v[162:163], v[126:127], s[34:35] op_sel_hi:[1,0]
	v_pk_mul_f32 v[122:123], v[122:123], v[126:127]
	v_pk_mul_f32 v[126:127], v[128:129], s[34:35] op_sel_hi:[1,0]
	v_exp_f32_e32 v162, v162
	v_exp_f32_e32 v163, v163
	v_exp_f32_e32 v126, v126
	v_exp_f32_e32 v127, v127
	v_pk_mul_f32 v[124:125], v[124:125], v[128:129]
	v_pk_add_f32 v[162:163], v[162:163], 1.0 op_sel_hi:[1,0]
	v_pk_mul_f32 v[106:107], v[106:107], v[110:111]
	v_pk_add_f32 v[126:127], v[126:127], 1.0 op_sel_hi:[1,0]
	v_rcp_f32_e32 v162, v162
	v_rcp_f32_e32 v163, v163
	v_rcp_f32_e32 v126, v126
	v_rcp_f32_e32 v127, v127
	v_lshl_or_b32 v130, s40, 7, v156
	v_pk_mul_f32 v[122:123], v[122:123], v[162:163]
	v_pk_mul_f32 v[120:121], v[120:121], v[116:117]
	v_pk_mul_f32 v[124:125], v[124:125], v[126:127]
	v_cvt_pk_bf16_f32 v122, v122, v123
	v_lshl_add_u32 v158, s64, 8, v141
	v_cvt_pk_bf16_f32 v123, v124, v125
	v_pk_mul_f32 v[124:125], v[114:115], s[34:35] op_sel_hi:[1,0]
	v_pk_mul_f32 v[114:115], v[118:119], v[114:115]
	v_exp_f32_e32 v124, v124
	v_exp_f32_e32 v125, v125
	v_pk_mul_f32 v[118:119], v[110:111], s[34:35] op_sel_hi:[1,0]
	v_pk_mul_f32 v[110:111], v[112:113], s[34:35] op_sel_hi:[1,0]
	v_exp_f32_e32 v118, v118
	v_pk_add_f32 v[124:125], v[124:125], 1.0 op_sel_hi:[1,0]
	v_exp_f32_e32 v119, v119
	v_rcp_f32_e32 v124, v124
	v_rcp_f32_e32 v125, v125
	v_exp_f32_e32 v110, v110
	v_exp_f32_e32 v111, v111
	v_pk_add_f32 v[118:119], v[118:119], 1.0 op_sel_hi:[1,0]
	v_pk_mul_f32 v[114:115], v[114:115], v[124:125]
	v_rcp_f32_e32 v118, v118
	v_cvt_pk_bf16_f32 v124, v114, v115
	v_pk_mul_f32 v[114:115], v[116:117], s[34:35] op_sel_hi:[1,0]
	v_pk_add_f32 v[110:111], v[110:111], 1.0 op_sel_hi:[1,0]
	v_exp_f32_e32 v114, v114
	v_exp_f32_e32 v115, v115
	v_rcp_f32_e32 v119, v119
	v_rcp_f32_e32 v110, v110
	v_rcp_f32_e32 v111, v111
	v_pk_add_f32 v[114:115], v[114:115], 1.0 op_sel_hi:[1,0]
	v_ashrrev_i32_e32 v131, 31, v130
	v_rcp_f32_e32 v114, v114
	v_rcp_f32_e32 v115, v115
	v_mov_b64_e32 v[154:155], s[62:63]
	s_movk_i32 s20, 0x1600
	v_mad_i64_i32 v[132:133], s[2:3], v158, s20, v[154:155]
	v_pk_mul_f32 v[114:115], v[120:121], v[114:115]
	v_pk_mul_f32 v[108:109], v[108:109], v[112:113]
	v_cvt_pk_bf16_f32 v125, v114, v115
	v_lshlrev_b64 v[114:115], 1, v[130:131]
	v_lshl_add_u64 v[116:117], v[132:133], 0, v[114:115]
	v_pk_mul_f32 v[106:107], v[106:107], v[118:119]
	v_pk_mul_f32 v[108:109], v[108:109], v[110:111]
	global_store_dwordx4 v[116:117], v[122:125], off
	v_cvt_pk_bf16_f32 v106, v106, v107
	v_cvt_pk_bf16_f32 v107, v108, v109
	v_pk_mul_f32 v[108:109], v[98:99], s[34:35] op_sel_hi:[1,0]
	v_pk_mul_f32 v[98:99], v[102:103], v[98:99]
	v_exp_f32_e32 v108, v108
	v_exp_f32_e32 v109, v109
	v_pk_mul_f32 v[104:105], v[104:105], v[100:101]
	v_pk_mul_f32 v[90:91], v[90:91], v[94:95]
	v_or_b32_e32 v116, 16, v158
	v_pk_add_f32 v[108:109], v[108:109], 1.0 op_sel_hi:[1,0]
	v_mad_i64_i32 v[116:117], s[2:3], v116, s20, v[154:155]
	v_rcp_f32_e32 v108, v108
	v_rcp_f32_e32 v109, v109
	v_pk_mul_f32 v[92:93], v[92:93], v[96:97]
	v_pk_mul_f32 v[88:89], v[88:89], v[84:85]
	v_pk_mul_f32 v[74:75], v[74:75], v[78:79]
	v_pk_mul_f32 v[98:99], v[98:99], v[108:109]
	v_pk_mul_f32 v[76:77], v[76:77], v[80:81]
	v_cvt_pk_bf16_f32 v108, v98, v99
	v_pk_mul_f32 v[98:99], v[100:101], s[34:35] op_sel_hi:[1,0]
	v_pk_mul_f32 v[100:101], v[94:95], s[34:35] op_sel_hi:[1,0]
	v_exp_f32_e32 v98, v98
	v_exp_f32_e32 v99, v99
	v_pk_mul_f32 v[94:95], v[96:97], s[34:35] op_sel_hi:[1,0]
	v_exp_f32_e32 v100, v100
	v_exp_f32_e32 v101, v101
	v_exp_f32_e32 v94, v94
	v_exp_f32_e32 v95, v95
	v_pk_add_f32 v[98:99], v[98:99], 1.0 op_sel_hi:[1,0]
	v_pk_add_f32 v[100:101], v[100:101], 1.0 op_sel_hi:[1,0]
	v_rcp_f32_e32 v98, v98
	v_rcp_f32_e32 v99, v99
	v_pk_add_f32 v[94:95], v[94:95], 1.0 op_sel_hi:[1,0]
	v_rcp_f32_e32 v100, v100
	v_rcp_f32_e32 v101, v101
	v_rcp_f32_e32 v94, v94
	v_rcp_f32_e32 v95, v95
	v_pk_mul_f32 v[98:99], v[104:105], v[98:99]
	v_pk_mul_f32 v[90:91], v[90:91], v[100:101]
	v_cvt_pk_bf16_f32 v109, v98, v99
	v_lshl_add_u64 v[98:99], v[116:117], 0, v[114:115]
	v_pk_mul_f32 v[92:93], v[92:93], v[94:95]
	global_store_dwordx4 v[98:99], v[106:109], off
	v_cvt_pk_bf16_f32 v90, v90, v91
	v_cvt_pk_bf16_f32 v91, v92, v93
	v_pk_mul_f32 v[92:93], v[82:83], s[34:35] op_sel_hi:[1,0]
	v_pk_mul_f32 v[82:83], v[86:87], v[82:83]
	v_exp_f32_e32 v92, v92
	v_exp_f32_e32 v93, v93
	v_or_b32_e32 v98, 32, v158
	v_mad_i64_i32 v[98:99], s[2:3], v98, s20, v[154:155]
	v_pk_add_f32 v[92:93], v[92:93], 1.0 op_sel_hi:[1,0]
	v_pk_mul_f32 v[72:73], v[72:73], v[68:69]
	v_rcp_f32_e32 v92, v92
	v_rcp_f32_e32 v93, v93
	v_pk_mul_f32 v[58:59], v[58:59], v[62:63]
	v_pk_mul_f32 v[60:61], v[60:61], v[64:65]
	v_pk_mul_f32 v[56:57], v[56:57], v[52:53]
	v_pk_mul_f32 v[82:83], v[82:83], v[92:93]
	v_pk_mul_f32 v[42:43], v[42:43], v[46:47]
	v_cvt_pk_bf16_f32 v92, v82, v83
	v_pk_mul_f32 v[82:83], v[84:85], s[34:35] op_sel_hi:[1,0]
	v_pk_mul_f32 v[84:85], v[78:79], s[34:35] op_sel_hi:[1,0]
	v_exp_f32_e32 v82, v82
	v_exp_f32_e32 v83, v83
	v_pk_mul_f32 v[78:79], v[80:81], s[34:35] op_sel_hi:[1,0]
	v_exp_f32_e32 v84, v84
	v_exp_f32_e32 v85, v85
	v_exp_f32_e32 v78, v78
	v_exp_f32_e32 v79, v79
	v_pk_add_f32 v[82:83], v[82:83], 1.0 op_sel_hi:[1,0]
	v_pk_add_f32 v[84:85], v[84:85], 1.0 op_sel_hi:[1,0]
	v_rcp_f32_e32 v82, v82
	v_rcp_f32_e32 v83, v83
	v_pk_add_f32 v[78:79], v[78:79], 1.0 op_sel_hi:[1,0]
	v_rcp_f32_e32 v84, v84
	v_rcp_f32_e32 v85, v85
	v_rcp_f32_e32 v78, v78
	v_rcp_f32_e32 v79, v79
	v_pk_mul_f32 v[82:83], v[88:89], v[82:83]
	v_pk_mul_f32 v[74:75], v[74:75], v[84:85]
	v_cvt_pk_bf16_f32 v93, v82, v83
	v_lshl_add_u64 v[82:83], v[98:99], 0, v[114:115]
	v_pk_mul_f32 v[76:77], v[76:77], v[78:79]
	global_store_dwordx4 v[82:83], v[90:93], off
	v_cvt_pk_bf16_f32 v74, v74, v75
	v_cvt_pk_bf16_f32 v75, v76, v77
	v_pk_mul_f32 v[76:77], v[66:67], s[34:35] op_sel_hi:[1,0]
	v_pk_mul_f32 v[66:67], v[70:71], v[66:67]
	v_exp_f32_e32 v76, v76
	v_exp_f32_e32 v77, v77
	v_or_b32_e32 v82, 48, v158
	v_mad_i64_i32 v[82:83], s[2:3], v82, s20, v[154:155]
	v_pk_add_f32 v[76:77], v[76:77], 1.0 op_sel_hi:[1,0]
	v_pk_mul_f32 v[44:45], v[44:45], v[48:49]
	v_rcp_f32_e32 v76, v76
	v_rcp_f32_e32 v77, v77
	v_pk_mul_f32 v[40:41], v[40:41], v[36:37]
	v_pk_mul_f32 v[26:27], v[26:27], v[30:31]
	v_pk_mul_f32 v[28:29], v[28:29], v[32:33]
	v_pk_mul_f32 v[66:67], v[66:67], v[76:77]
	v_pk_mul_f32 v[24:25], v[24:25], v[20:21]
	v_cvt_pk_bf16_f32 v76, v66, v67
	v_pk_mul_f32 v[66:67], v[68:69], s[34:35] op_sel_hi:[1,0]
	v_pk_mul_f32 v[68:69], v[62:63], s[34:35] op_sel_hi:[1,0]
	v_exp_f32_e32 v66, v66
	v_exp_f32_e32 v67, v67
	v_pk_mul_f32 v[62:63], v[64:65], s[34:35] op_sel_hi:[1,0]
	v_exp_f32_e32 v68, v68
	v_exp_f32_e32 v69, v69
	v_exp_f32_e32 v62, v62
	v_exp_f32_e32 v63, v63
	v_pk_add_f32 v[66:67], v[66:67], 1.0 op_sel_hi:[1,0]
	v_pk_add_f32 v[68:69], v[68:69], 1.0 op_sel_hi:[1,0]
	v_rcp_f32_e32 v66, v66
	v_rcp_f32_e32 v67, v67
	v_pk_add_f32 v[62:63], v[62:63], 1.0 op_sel_hi:[1,0]
	v_rcp_f32_e32 v68, v68
	v_rcp_f32_e32 v69, v69
	v_rcp_f32_e32 v62, v62
	v_rcp_f32_e32 v63, v63
	v_pk_mul_f32 v[66:67], v[72:73], v[66:67]
	v_pk_mul_f32 v[58:59], v[58:59], v[68:69]
	v_cvt_pk_bf16_f32 v77, v66, v67
	v_lshl_add_u64 v[66:67], v[82:83], 0, v[114:115]
	v_pk_mul_f32 v[60:61], v[60:61], v[62:63]
	global_store_dwordx4 v[66:67], v[74:77], off
	v_cvt_pk_bf16_f32 v58, v58, v59
	v_cvt_pk_bf16_f32 v59, v60, v61
	v_pk_mul_f32 v[60:61], v[50:51], s[34:35] op_sel_hi:[1,0]
	v_pk_mul_f32 v[50:51], v[54:55], v[50:51]
	v_exp_f32_e32 v60, v60
	v_exp_f32_e32 v61, v61
	v_add_u32_e32 v66, 0x80, v158
	v_mad_i64_i32 v[66:67], s[2:3], v66, s20, v[154:155]
	v_pk_add_f32 v[60:61], v[60:61], 1.0 op_sel_hi:[1,0]
	v_pk_mul_f32 v[10:11], v[10:11], v[14:15]
	v_rcp_f32_e32 v60, v60
	v_rcp_f32_e32 v61, v61
	v_pk_mul_f32 v[12:13], v[12:13], v[16:17]
	v_pk_mul_f32 v[2:3], v[2:3], v[6:7]
	v_pk_mul_f32 v[4:5], v[4:5], v[8:9]
	v_pk_mul_f32 v[50:51], v[50:51], v[60:61]
	s_nop 0
	v_cvt_pk_bf16_f32 v60, v50, v51
	v_pk_mul_f32 v[50:51], v[52:53], s[34:35] op_sel_hi:[1,0]
	v_pk_mul_f32 v[52:53], v[46:47], s[34:35] op_sel_hi:[1,0]
	v_exp_f32_e32 v50, v50
	v_exp_f32_e32 v51, v51
	v_pk_mul_f32 v[46:47], v[48:49], s[34:35] op_sel_hi:[1,0]
	v_exp_f32_e32 v52, v52
	v_exp_f32_e32 v53, v53
	v_exp_f32_e32 v46, v46
	v_exp_f32_e32 v47, v47
	v_pk_add_f32 v[50:51], v[50:51], 1.0 op_sel_hi:[1,0]
	v_pk_add_f32 v[52:53], v[52:53], 1.0 op_sel_hi:[1,0]
	v_rcp_f32_e32 v50, v50
	v_rcp_f32_e32 v51, v51
	v_pk_add_f32 v[46:47], v[46:47], 1.0 op_sel_hi:[1,0]
	v_rcp_f32_e32 v52, v52
	v_rcp_f32_e32 v53, v53
	v_rcp_f32_e32 v46, v46
	v_rcp_f32_e32 v47, v47
	v_pk_mul_f32 v[50:51], v[56:57], v[50:51]
	v_pk_mul_f32 v[42:43], v[42:43], v[52:53]
	v_cvt_pk_bf16_f32 v61, v50, v51
	v_lshl_add_u64 v[50:51], v[66:67], 0, v[114:115]
	v_pk_mul_f32 v[44:45], v[44:45], v[46:47]
	global_store_dwordx4 v[50:51], v[58:61], off
	v_cvt_pk_bf16_f32 v42, v42, v43
	v_cvt_pk_bf16_f32 v43, v44, v45
	v_pk_mul_f32 v[44:45], v[34:35], s[34:35] op_sel_hi:[1,0]
	v_pk_mul_f32 v[34:35], v[38:39], v[34:35]
	v_exp_f32_e32 v44, v44
	v_exp_f32_e32 v45, v45
	v_add_u32_e32 v50, 0x90, v158
	v_mad_i64_i32 v[50:51], s[2:3], v50, s20, v[154:155]
	v_pk_add_f32 v[44:45], v[44:45], 1.0 op_sel_hi:[1,0]
	s_nop 0
	v_rcp_f32_e32 v44, v44
	v_rcp_f32_e32 v45, v45
	s_nop 0
	v_pk_mul_f32 v[34:35], v[34:35], v[44:45]
	s_nop 0
	v_cvt_pk_bf16_f32 v44, v34, v35
	v_pk_mul_f32 v[34:35], v[36:37], s[34:35] op_sel_hi:[1,0]
	v_pk_mul_f32 v[36:37], v[30:31], s[34:35] op_sel_hi:[1,0]
	v_exp_f32_e32 v34, v34
	v_exp_f32_e32 v35, v35
	v_pk_mul_f32 v[30:31], v[32:33], s[34:35] op_sel_hi:[1,0]
	v_exp_f32_e32 v36, v36
	v_exp_f32_e32 v37, v37
	v_exp_f32_e32 v30, v30
	v_exp_f32_e32 v31, v31
	v_pk_add_f32 v[34:35], v[34:35], 1.0 op_sel_hi:[1,0]
	v_pk_add_f32 v[36:37], v[36:37], 1.0 op_sel_hi:[1,0]
	v_rcp_f32_e32 v34, v34
	v_rcp_f32_e32 v35, v35
	v_pk_add_f32 v[30:31], v[30:31], 1.0 op_sel_hi:[1,0]
	v_rcp_f32_e32 v36, v36
	v_rcp_f32_e32 v37, v37
	v_rcp_f32_e32 v30, v30
	v_rcp_f32_e32 v31, v31
	v_pk_mul_f32 v[34:35], v[40:41], v[34:35]
	v_pk_mul_f32 v[26:27], v[26:27], v[36:37]
	v_cvt_pk_bf16_f32 v45, v34, v35
	v_lshl_add_u64 v[34:35], v[50:51], 0, v[114:115]
	v_pk_mul_f32 v[28:29], v[28:29], v[30:31]
	global_store_dwordx4 v[34:35], v[42:45], off
	v_cvt_pk_bf16_f32 v26, v26, v27
	v_cvt_pk_bf16_f32 v27, v28, v29
	v_pk_mul_f32 v[28:29], v[18:19], s[34:35] op_sel_hi:[1,0]
	v_pk_mul_f32 v[18:19], v[22:23], v[18:19]
	v_exp_f32_e32 v28, v28
	v_exp_f32_e32 v29, v29
	v_add_u32_e32 v34, 0xa0, v158
	v_mad_i64_i32 v[34:35], s[2:3], v34, s20, v[154:155]
	v_pk_add_f32 v[28:29], v[28:29], 1.0 op_sel_hi:[1,0]
	s_nop 0
	v_rcp_f32_e32 v28, v28
	v_rcp_f32_e32 v29, v29
	s_nop 0
	v_pk_mul_f32 v[18:19], v[18:19], v[28:29]
	s_nop 0
	v_cvt_pk_bf16_f32 v28, v18, v19
	v_pk_mul_f32 v[18:19], v[20:21], s[34:35] op_sel_hi:[1,0]
	v_pk_mul_f32 v[20:21], v[14:15], s[34:35] op_sel_hi:[1,0]
	v_exp_f32_e32 v18, v18
	v_exp_f32_e32 v19, v19
	v_pk_mul_f32 v[14:15], v[16:17], s[34:35] op_sel_hi:[1,0]
	v_exp_f32_e32 v20, v20
	v_exp_f32_e32 v21, v21
	v_exp_f32_e32 v14, v14
	v_exp_f32_e32 v15, v15
	v_pk_add_f32 v[18:19], v[18:19], 1.0 op_sel_hi:[1,0]
	v_pk_add_f32 v[20:21], v[20:21], 1.0 op_sel_hi:[1,0]
	v_rcp_f32_e32 v18, v18
	v_rcp_f32_e32 v19, v19
	v_pk_add_f32 v[14:15], v[14:15], 1.0 op_sel_hi:[1,0]
	v_rcp_f32_e32 v20, v20
	v_rcp_f32_e32 v21, v21
	v_rcp_f32_e32 v14, v14
	v_rcp_f32_e32 v15, v15
	v_pk_mul_f32 v[18:19], v[24:25], v[18:19]
	v_pk_mul_f32 v[10:11], v[10:11], v[20:21]
	v_cvt_pk_bf16_f32 v29, v18, v19
	v_lshl_add_u64 v[18:19], v[34:35], 0, v[114:115]
	v_pk_mul_f32 v[12:13], v[12:13], v[14:15]
	global_store_dwordx4 v[18:19], v[26:29], off
	v_cvt_pk_bf16_f32 v10, v10, v11
	v_cvt_pk_bf16_f32 v11, v12, v13
	v_pk_mul_f32 v[12:13], v[6:7], s[34:35] op_sel_hi:[1,0]
	v_add_u32_e32 v18, 0xb0, v158
	v_exp_f32_e32 v12, v12
	v_exp_f32_e32 v13, v13
	v_mad_i64_i32 v[18:19], s[2:3], v18, s20, v[154:155]
	v_pk_add_f32 v[12:13], v[12:13], 1.0 op_sel_hi:[1,0]
	s_nop 0
	v_rcp_f32_e32 v12, v12
	v_rcp_f32_e32 v13, v13
	s_nop 0
	v_pk_mul_f32 v[2:3], v[2:3], v[12:13]
	s_nop 0
	v_cvt_pk_bf16_f32 v12, v2, v3
	v_pk_mul_f32 v[2:3], v[8:9], s[34:35] op_sel_hi:[1,0]
	s_nop 0
	v_exp_f32_e32 v2, v2
	v_exp_f32_e32 v3, v3
	s_nop 0
	v_pk_add_f32 v[2:3], v[2:3], 1.0 op_sel_hi:[1,0]
	s_nop 0
	v_rcp_f32_e32 v2, v2
	v_rcp_f32_e32 v3, v3
	s_nop 0
	v_pk_mul_f32 v[2:3], v[4:5], v[2:3]
	s_nop 0
	v_cvt_pk_bf16_f32 v13, v2, v3
	v_lshl_add_u64 v[2:3], v[18:19], 0, v[114:115]
	global_store_dwordx4 v[2:3], v[10:13], off
	s_branch .LBB0_429

.LBB0_503:
.LBB0_504:
	s_setprio 0
	s_add_i32 s33, s41, 1
	s_cmp_eq_u32 s41, 10
	s_cbranch_scc1 .LBB0_571
	s_cmp_ge_i32 s33, s40
	s_cbranch_scc1 .LBB0_571
